# SwiGLU epilogue: row-rms loads hoisted before the K-loop, epilogue starts without a vmcnt drain; tile prefetch retired behind the epilogue stores instead
# baseline (speedup 1.0000x reference)
.LBB0_102:
	v_lshl_add_u32 v248, s22, 8, v146
	v_lshlrev_b32_e32 v248, 2, v248
	global_load_dword v230, v248, s[80:81]
	global_load_dword v231, v248, s[80:81] offset:64
	global_load_dword v232, v248, s[80:81] offset:128
	global_load_dword v233, v248, s[80:81] offset:192
	global_load_dword v234, v248, s[80:81] offset:512
	global_load_dword v235, v248, s[80:81] offset:576
	global_load_dword v236, v248, s[80:81] offset:640
	global_load_dword v237, v248, s[80:81] offset:704
	s_ashr_i32 s17, s16, 31
	s_lshl_b64 s[0:1], s[16:17], 20
	s_add_u32 s18, s26, s0
	s_addc_u32 s19, s27, s1
	s_and_b64 s[0:1], s[6:7], exec
	s_cselect_b32 s17, s19, s25
	s_cselect_b32 s51, s18, s24
	s_ashr_i32 s15, s14, 31
	s_lshl_b64 s[0:1], s[14:15], 20
	s_add_u32 s20, s36, s0
	s_addc_u32 s21, s37, s1
	s_and_b64 s[0:1], s[6:7], exec
	s_cselect_b32 s15, s21, s29
	s_cselect_b32 s34, s20, s28
	s_add_u32 s24, s24, 0x80080
	s_addc_u32 s25, s25, 0
	s_add_u32 s35, s28, 0x100
	s_addc_u32 s52, s29, 0
	s_mov_b32 s61, -2
	s_add_u32 s0, s24, 0xfff80080
	s_addc_u32 s1, s25, -1
	s_add_i32 s59, 0, 0x10000
	s_cmp_eq_u32 s61, 28
	s_cselect_b32 s31, s17, s1
	s_cselect_b32 s30, s51, s0
	s_cselect_b32 s29, s15, s52
	s_cselect_b32 s28, s34, s35
	s_add_i32 s63, 0, 0x14000
	v_add_u32_e32 v154, s59, v147
	v_add_u32_e32 v170, s63, v147
	ds_read_b128 v[138:141], v154
	ds_read_b128 v[142:145], v154 offset:1024
	ds_read_b128 v[150:153], v154 offset:2048
	ds_read_b128 v[154:157], v154 offset:3072
	ds_read_b128 v[158:161], v170
	ds_read_b128 v[162:165], v170 offset:1024
	ds_read_b128 v[166:169], v170 offset:2048
	ds_read_b128 v[170:173], v170 offset:3072
	v_lshl_add_u64 v[220:221], s[24:25], 0, v[134:135]
	s_add_i32 m0, s40, 0xc000
	ds_read_b128 v[174:177], v149
	ds_read_b128 v[178:181], v149 offset:1024
	ds_read_b128 v[182:185], v149 offset:2048
	ds_read_b128 v[186:189], v149 offset:3072
	ds_read_b128 v[190:193], v149 offset:4096
	ds_read_b128 v[194:197], v149 offset:5120
	ds_read_b128 v[212:215], v149 offset:6144
	ds_read_b128 v[216:219], v149 offset:7168
	global_load_lds_dwordx4 v[220:221], off
	v_lshl_add_u64 v[220:221], s[24:25], 0, v[136:137]
	s_add_i32 m0, s40, 0xe000
	s_nop 0
	global_load_lds_dwordx4 v[220:221], off
	s_waitcnt vmcnt(63)
	s_waitcnt lgkmcnt(0)
	s_barrier
	s_setprio 1
	s_waitcnt lgkmcnt(0)
	v_mfma_f32_16x16x32_bf16 v[124:127], v[138:141], v[174:177], 0
	v_mfma_f32_16x16x32_bf16 v[116:119], v[150:153], v[174:177], 0
	v_mfma_f32_16x16x32_bf16 v[108:111], v[138:141], v[182:185], 0
	v_mfma_f32_16x16x32_bf16 v[96:99], v[150:153], v[182:185], 0
	v_mfma_f32_16x16x32_bf16 v[88:91], v[138:141], v[190:193], 0
	v_mfma_f32_16x16x32_bf16 v[80:83], v[150:153], v[190:193], 0
	v_mfma_f32_16x16x32_bf16 v[72:75], v[138:141], v[212:215], 0
	v_mfma_f32_16x16x32_bf16 v[64:67], v[150:153], v[212:215], 0
	v_mfma_f32_16x16x32_bf16 v[124:127], v[142:145], v[178:181], v[124:127]
	v_mfma_f32_16x16x32_bf16 v[116:119], v[154:157], v[178:181], v[116:119]
	v_mfma_f32_16x16x32_bf16 v[108:111], v[142:145], v[186:189], v[108:111]
	v_mfma_f32_16x16x32_bf16 v[96:99], v[154:157], v[186:189], v[96:99]
	v_mfma_f32_16x16x32_bf16 v[88:91], v[142:145], v[194:197], v[88:91]
	v_mfma_f32_16x16x32_bf16 v[80:83], v[154:157], v[194:197], v[80:83]
	v_mfma_f32_16x16x32_bf16 v[72:75], v[142:145], v[216:219], v[72:75]
	v_mfma_f32_16x16x32_bf16 v[64:67], v[154:157], v[216:219], v[64:67]
	s_setprio 0
	s_setprio 1
	v_mfma_f32_16x16x32_bf16 v[120:123], v[158:161], v[174:177], 0
	v_mfma_f32_16x16x32_bf16 v[112:115], v[166:169], v[174:177], 0
	v_mfma_f32_16x16x32_bf16 v[104:107], v[158:161], v[182:185], 0
	v_mfma_f32_16x16x32_bf16 v[100:103], v[166:169], v[182:185], 0
	v_mfma_f32_16x16x32_bf16 v[92:95], v[158:161], v[190:193], 0
	v_mfma_f32_16x16x32_bf16 v[84:87], v[166:169], v[190:193], 0
	v_mfma_f32_16x16x32_bf16 v[76:79], v[158:161], v[212:215], 0
	v_mfma_f32_16x16x32_bf16 v[68:71], v[166:169], v[212:215], 0
	v_mfma_f32_16x16x32_bf16 v[120:123], v[162:165], v[178:181], v[120:123]
	v_mfma_f32_16x16x32_bf16 v[112:115], v[170:173], v[178:181], v[112:115]
	v_mfma_f32_16x16x32_bf16 v[104:107], v[162:165], v[186:189], v[104:107]
	v_mfma_f32_16x16x32_bf16 v[100:103], v[170:173], v[186:189], v[100:103]
	v_mfma_f32_16x16x32_bf16 v[92:95], v[162:165], v[194:197], v[92:95]
	v_mfma_f32_16x16x32_bf16 v[84:87], v[170:173], v[194:197], v[84:87]
	v_mfma_f32_16x16x32_bf16 v[76:79], v[162:165], v[216:219], v[76:79]
	v_mfma_f32_16x16x32_bf16 v[68:71], v[170:173], v[216:219], v[68:71]
	s_setprio 0
	s_barrier
	s_add_i32 s0, s59, s38
	v_lshl_add_u64 v[220:221], s[28:29], 0, v[198:199]
	s_mov_b32 m0, s0
	ds_read_b128 v[174:177], v149 offset:16384
	ds_read_b128 v[178:181], v149 offset:17408
	ds_read_b128 v[182:185], v149 offset:18432
	ds_read_b128 v[186:189], v149 offset:19456
	ds_read_b128 v[190:193], v149 offset:20480
	ds_read_b128 v[194:197], v149 offset:21504
	ds_read_b128 v[212:215], v149 offset:22528
	ds_read_b128 v[216:219], v149 offset:23552
	global_load_lds_dwordx4 v[220:221], off
	s_add_i32 m0, s0, 0x2000
	s_add_u32 s0, s28, 0x80000
	v_lshl_add_u64 v[222:223], s[28:29], 0, v[128:129]
	s_addc_u32 s1, s29, 0
	s_add_i32 s59, s63, s38
	global_load_lds_dwordx4 v[222:223], off
	v_lshl_add_u64 v[224:225], s[0:1], 0, v[198:199]
	s_mov_b32 m0, s59
	v_lshl_add_u64 v[226:227], s[30:31], 0, v[130:131]
	global_load_lds_dwordx4 v[224:225], off
	v_lshl_add_u64 v[224:225], s[0:1], 0, v[128:129]
	s_add_i32 m0, s59, 0x2000
	s_nop 0
	global_load_lds_dwordx4 v[224:225], off
	v_lshl_add_u64 v[224:225], s[30:31], 0, v[132:133]
	s_mov_b32 m0, s40
	s_nop 0
	global_load_lds_dwordx4 v[224:225], off
	s_mov_b32 m0, s41
	s_nop 0
	global_load_lds_dwordx4 v[226:227], off
	s_waitcnt vmcnt(63)
	s_waitcnt lgkmcnt(0)
	s_barrier
	s_setprio 1
	s_waitcnt lgkmcnt(0)
	v_mfma_f32_16x16x32_bf16 v[56:59], v[138:141], v[174:177], 0
	v_mfma_f32_16x16x32_bf16 v[48:51], v[150:153], v[174:177], 0
	v_mfma_f32_16x16x32_bf16 v[40:43], v[138:141], v[182:185], 0
	v_mfma_f32_16x16x32_bf16 v[32:35], v[150:153], v[182:185], 0
	v_mfma_f32_16x16x32_bf16 v[24:27], v[138:141], v[190:193], 0
	v_mfma_f32_16x16x32_bf16 v[16:19], v[150:153], v[190:193], 0
	v_mfma_f32_16x16x32_bf16 v[8:11], v[138:141], v[212:215], 0
	v_mfma_f32_16x16x32_bf16 v[0:3], v[150:153], v[212:215], 0
	v_mfma_f32_16x16x32_bf16 v[56:59], v[142:145], v[178:181], v[56:59]
	v_mfma_f32_16x16x32_bf16 v[48:51], v[154:157], v[178:181], v[48:51]
	v_mfma_f32_16x16x32_bf16 v[40:43], v[142:145], v[186:189], v[40:43]
	v_mfma_f32_16x16x32_bf16 v[32:35], v[154:157], v[186:189], v[32:35]
	v_mfma_f32_16x16x32_bf16 v[24:27], v[142:145], v[194:197], v[24:27]
	v_mfma_f32_16x16x32_bf16 v[16:19], v[154:157], v[194:197], v[16:19]
	v_mfma_f32_16x16x32_bf16 v[8:11], v[142:145], v[216:219], v[8:11]
	v_mfma_f32_16x16x32_bf16 v[0:3], v[154:157], v[216:219], v[0:3]
	s_setprio 0
	s_setprio 1
	v_mfma_f32_16x16x32_bf16 v[60:63], v[158:161], v[174:177], 0
	v_mfma_f32_16x16x32_bf16 v[52:55], v[166:169], v[174:177], 0
	v_mfma_f32_16x16x32_bf16 v[44:47], v[158:161], v[182:185], 0
	v_mfma_f32_16x16x32_bf16 v[36:39], v[166:169], v[182:185], 0
	v_mfma_f32_16x16x32_bf16 v[28:31], v[158:161], v[190:193], 0
	v_mfma_f32_16x16x32_bf16 v[20:23], v[166:169], v[190:193], 0
	v_mfma_f32_16x16x32_bf16 v[12:15], v[158:161], v[212:215], 0
	v_mfma_f32_16x16x32_bf16 v[4:7], v[166:169], v[212:215], 0
	v_mfma_f32_16x16x32_bf16 v[60:63], v[162:165], v[178:181], v[60:63]
	v_mfma_f32_16x16x32_bf16 v[52:55], v[170:173], v[178:181], v[52:55]
	v_mfma_f32_16x16x32_bf16 v[44:47], v[162:165], v[186:189], v[44:47]
	v_mfma_f32_16x16x32_bf16 v[36:39], v[170:173], v[186:189], v[36:39]
	v_mfma_f32_16x16x32_bf16 v[28:31], v[162:165], v[194:197], v[28:31]
	v_mfma_f32_16x16x32_bf16 v[20:23], v[170:173], v[194:197], v[20:23]
	v_mfma_f32_16x16x32_bf16 v[12:15], v[162:165], v[216:219], v[12:15]
	v_mfma_f32_16x16x32_bf16 v[4:7], v[170:173], v[216:219], v[4:7]
	s_setprio 0
	s_barrier
	s_add_i32 s59, 0, 0x18000
	s_add_i32 s63, 0, 0x1c000
	v_add_u32_e32 v154, s59, v147
	v_add_u32_e32 v170, s63, v147
	ds_read_b128 v[138:141], v154
	ds_read_b128 v[142:145], v154 offset:1024
	ds_read_b128 v[150:153], v154 offset:2048
	ds_read_b128 v[154:157], v154 offset:3072
	ds_read_b128 v[158:161], v170
	ds_read_b128 v[162:165], v170 offset:1024
	ds_read_b128 v[166:169], v170 offset:2048
	ds_read_b128 v[170:173], v170 offset:3072
	s_add_u32 s0, s30, 0x80000
	s_addc_u32 s1, s31, 0
	s_mov_b32 m0, s42
	v_lshl_add_u64 v[228:229], s[0:1], 0, v[132:133]
	ds_read_b128 v[174:177], v149 offset:32768
	ds_read_b128 v[178:181], v149 offset:33792
	ds_read_b128 v[182:185], v149 offset:34816
	ds_read_b128 v[186:189], v149 offset:35840
	ds_read_b128 v[190:193], v149 offset:36864
	ds_read_b128 v[194:197], v149 offset:37888
	ds_read_b128 v[212:215], v149 offset:38912
	ds_read_b128 v[216:219], v149 offset:39936
	global_load_lds_dwordx4 v[228:229], off
	v_lshl_add_u64 v[228:229], s[0:1], 0, v[130:131]
	s_mov_b32 m0, s43
	s_nop 0
	global_load_lds_dwordx4 v[228:229], off
	s_waitcnt vmcnt(8)
	s_waitcnt lgkmcnt(0)
	s_barrier
	s_setprio 1
	s_waitcnt lgkmcnt(0)
	v_mfma_f32_16x16x32_bf16 v[124:127], v[138:141], v[174:177], v[124:127]
	v_mfma_f32_16x16x32_bf16 v[116:119], v[150:153], v[174:177], v[116:119]
	v_mfma_f32_16x16x32_bf16 v[108:111], v[138:141], v[182:185], v[108:111]
	v_mfma_f32_16x16x32_bf16 v[96:99], v[150:153], v[182:185], v[96:99]
	v_mfma_f32_16x16x32_bf16 v[88:91], v[138:141], v[190:193], v[88:91]
	v_mfma_f32_16x16x32_bf16 v[80:83], v[150:153], v[190:193], v[80:83]
	v_mfma_f32_16x16x32_bf16 v[72:75], v[138:141], v[212:215], v[72:75]
	v_mfma_f32_16x16x32_bf16 v[64:67], v[150:153], v[212:215], v[64:67]
	v_mfma_f32_16x16x32_bf16 v[124:127], v[142:145], v[178:181], v[124:127]
	v_mfma_f32_16x16x32_bf16 v[116:119], v[154:157], v[178:181], v[116:119]
	v_mfma_f32_16x16x32_bf16 v[108:111], v[142:145], v[186:189], v[108:111]
	v_mfma_f32_16x16x32_bf16 v[96:99], v[154:157], v[186:189], v[96:99]
	v_mfma_f32_16x16x32_bf16 v[88:91], v[142:145], v[194:197], v[88:91]
	v_mfma_f32_16x16x32_bf16 v[80:83], v[154:157], v[194:197], v[80:83]
	v_mfma_f32_16x16x32_bf16 v[72:75], v[142:145], v[216:219], v[72:75]
	v_mfma_f32_16x16x32_bf16 v[64:67], v[154:157], v[216:219], v[64:67]
	s_setprio 0
	s_setprio 1
	v_mfma_f32_16x16x32_bf16 v[120:123], v[158:161], v[174:177], v[120:123]
	v_mfma_f32_16x16x32_bf16 v[112:115], v[166:169], v[174:177], v[112:115]
	v_mfma_f32_16x16x32_bf16 v[104:107], v[158:161], v[182:185], v[104:107]
	v_mfma_f32_16x16x32_bf16 v[100:103], v[166:169], v[182:185], v[100:103]
	v_mfma_f32_16x16x32_bf16 v[92:95], v[158:161], v[190:193], v[92:95]
	v_mfma_f32_16x16x32_bf16 v[84:87], v[166:169], v[190:193], v[84:87]
	v_mfma_f32_16x16x32_bf16 v[76:79], v[158:161], v[212:215], v[76:79]
	v_mfma_f32_16x16x32_bf16 v[68:71], v[166:169], v[212:215], v[68:71]
	v_mfma_f32_16x16x32_bf16 v[120:123], v[162:165], v[178:181], v[120:123]
	v_mfma_f32_16x16x32_bf16 v[112:115], v[170:173], v[178:181], v[112:115]
	v_mfma_f32_16x16x32_bf16 v[104:107], v[162:165], v[186:189], v[104:107]
	v_mfma_f32_16x16x32_bf16 v[100:103], v[170:173], v[186:189], v[100:103]
	v_mfma_f32_16x16x32_bf16 v[92:95], v[162:165], v[194:197], v[92:95]
	v_mfma_f32_16x16x32_bf16 v[84:87], v[170:173], v[194:197], v[84:87]
	v_mfma_f32_16x16x32_bf16 v[76:79], v[162:165], v[216:219], v[76:79]
	v_mfma_f32_16x16x32_bf16 v[68:71], v[170:173], v[216:219], v[68:71]
	s_setprio 0
	s_barrier
	s_add_i32 s0, s59, s38
	v_lshl_add_u64 v[220:221], v[220:221], 0, s[54:55]
	s_mov_b32 m0, s0
	ds_read_b128 v[174:177], v149 offset:49152
	ds_read_b128 v[178:181], v149 offset:50176
	ds_read_b128 v[182:185], v149 offset:51200
	ds_read_b128 v[186:189], v149 offset:52224
	ds_read_b128 v[190:193], v149 offset:53248
	ds_read_b128 v[194:197], v149 offset:54272
	ds_read_b128 v[212:215], v149 offset:55296
	ds_read_b128 v[216:219], v149 offset:56320
	global_load_lds_dwordx4 v[220:221], off
	s_add_i32 m0, s0, 0x2000
	s_add_u32 s0, s28, 0x80080
	v_lshl_add_u64 v[220:221], v[222:223], 0, s[54:55]
	s_addc_u32 s1, s29, 0
	s_add_i32 s28, s63, s38
	global_load_lds_dwordx4 v[220:221], off
	v_lshl_add_u64 v[220:221], s[0:1], 0, v[198:199]
	s_mov_b32 m0, s28
	s_nop 0
	global_load_lds_dwordx4 v[220:221], off
	v_lshl_add_u64 v[220:221], s[0:1], 0, v[128:129]
	s_add_i32 m0, s28, 0x2000
	s_nop 0
	global_load_lds_dwordx4 v[220:221], off
	v_lshl_add_u64 v[220:221], v[224:225], 0, s[54:55]
	s_mov_b32 m0, s47
	s_nop 0
	global_load_lds_dwordx4 v[220:221], off
	v_lshl_add_u64 v[220:221], v[226:227], 0, s[54:55]
	s_mov_b32 m0, s48
	s_nop 0
	global_load_lds_dwordx4 v[220:221], off
	s_waitcnt vmcnt(8)
	s_waitcnt lgkmcnt(0)
	s_barrier
	s_setprio 1
	s_waitcnt lgkmcnt(0)
	v_mfma_f32_16x16x32_bf16 v[56:59], v[138:141], v[174:177], v[56:59]
	v_mfma_f32_16x16x32_bf16 v[48:51], v[150:153], v[174:177], v[48:51]
	v_mfma_f32_16x16x32_bf16 v[40:43], v[138:141], v[182:185], v[40:43]
	v_mfma_f32_16x16x32_bf16 v[32:35], v[150:153], v[182:185], v[32:35]
	v_mfma_f32_16x16x32_bf16 v[24:27], v[138:141], v[190:193], v[24:27]
	v_mfma_f32_16x16x32_bf16 v[16:19], v[150:153], v[190:193], v[16:19]
	v_mfma_f32_16x16x32_bf16 v[8:11], v[138:141], v[212:215], v[8:11]
	v_mfma_f32_16x16x32_bf16 v[0:3], v[150:153], v[212:215], v[0:3]
	v_mfma_f32_16x16x32_bf16 v[56:59], v[142:145], v[178:181], v[56:59]
	v_mfma_f32_16x16x32_bf16 v[48:51], v[154:157], v[178:181], v[48:51]
	v_mfma_f32_16x16x32_bf16 v[40:43], v[142:145], v[186:189], v[40:43]
	v_mfma_f32_16x16x32_bf16 v[32:35], v[154:157], v[186:189], v[32:35]
	v_mfma_f32_16x16x32_bf16 v[24:27], v[142:145], v[194:197], v[24:27]
	v_mfma_f32_16x16x32_bf16 v[16:19], v[154:157], v[194:197], v[16:19]
	v_mfma_f32_16x16x32_bf16 v[8:11], v[142:145], v[216:219], v[8:11]
	v_mfma_f32_16x16x32_bf16 v[0:3], v[154:157], v[216:219], v[0:3]
	s_setprio 0
	s_setprio 1
	v_mfma_f32_16x16x32_bf16 v[60:63], v[158:161], v[174:177], v[60:63]
	v_mfma_f32_16x16x32_bf16 v[52:55], v[166:169], v[174:177], v[52:55]
	v_mfma_f32_16x16x32_bf16 v[44:47], v[158:161], v[182:185], v[44:47]
	v_mfma_f32_16x16x32_bf16 v[36:39], v[166:169], v[182:185], v[36:39]
	v_mfma_f32_16x16x32_bf16 v[28:31], v[158:161], v[190:193], v[28:31]
	v_mfma_f32_16x16x32_bf16 v[20:23], v[166:169], v[190:193], v[20:23]
	v_mfma_f32_16x16x32_bf16 v[12:15], v[158:161], v[212:215], v[12:15]
	v_mfma_f32_16x16x32_bf16 v[4:7], v[166:169], v[212:215], v[4:7]
	v_mfma_f32_16x16x32_bf16 v[60:63], v[162:165], v[178:181], v[60:63]
	v_mfma_f32_16x16x32_bf16 v[52:55], v[170:173], v[178:181], v[52:55]
	v_mfma_f32_16x16x32_bf16 v[44:47], v[162:165], v[186:189], v[44:47]
	v_mfma_f32_16x16x32_bf16 v[36:39], v[170:173], v[186:189], v[36:39]
	v_mfma_f32_16x16x32_bf16 v[28:31], v[162:165], v[194:197], v[28:31]
	v_mfma_f32_16x16x32_bf16 v[20:23], v[170:173], v[194:197], v[20:23]
	v_mfma_f32_16x16x32_bf16 v[12:15], v[162:165], v[216:219], v[12:15]
	v_mfma_f32_16x16x32_bf16 v[4:7], v[170:173], v[216:219], v[4:7]
	s_setprio 0
	s_barrier
	s_add_i32 s61, s61, 2
	s_add_u32 s24, s24, 0x100
	s_addc_u32 s25, s25, 0
	s_add_u32 s35, s35, 0x100
	s_addc_u32 s52, s52, 0

.LBB0_106:
	v_lshl_add_u32 v158, s22, 8, v146
	v_ashrrev_i32_e32 v159, 31, v158
	v_lshl_add_u64 v[138:139], v[158:159], 2, s[80:81]
	v_mov_b32_e32 v157, v230
	v_mov_b32_e32 v154, v234
	v_mov_b32_e32 v152, v235
	v_or_b32_e32 v144, 16, v158
	v_ashrrev_i32_e32 v145, 31, v144
	v_lshl_add_u64 v[140:141], v[144:145], 2, s[80:81]
	v_mov_b32_e32 v159, v231
	v_or_b32_e32 v142, 32, v158
	v_ashrrev_i32_e32 v143, 31, v142
	v_lshl_add_u64 v[140:141], v[142:143], 2, s[80:81]
	v_mov_b32_e32 v156, v232
	v_or_b32_e32 v140, 48, v158
	v_ashrrev_i32_e32 v141, 31, v140
	v_lshl_add_u64 v[150:151], v[140:141], 2, s[80:81]
	v_mov_b32_e32 v155, v233
	v_mov_b32_e32 v143, v237
	v_pk_mul_f32 v[120:121], v[124:125], v[120:121]
	v_mov_b32_e32 v150, v236
	v_pk_mul_f32 v[112:113], v[116:117], v[112:113]
	v_pk_mul_f32 v[114:115], v[118:119], v[114:115]
	v_lshl_or_b32 v138, s23, 7, v148
	v_pk_mul_f32 v[122:123], v[126:127], v[122:123]
	v_ashrrev_i32_e32 v139, 31, v138
	v_lshl_add_u64 v[138:139], v[138:139], 1, s[10:11]
	v_pk_mul_f32 v[104:105], v[108:109], v[104:105]
	v_pk_mul_f32 v[100:101], v[96:97], v[100:101]
	v_pk_mul_f32 v[102:103], v[98:99], v[102:103]
	v_pk_mul_f32 v[106:107], v[110:111], v[106:107]
	v_pk_mul_f32 v[92:93], v[88:89], v[92:93]
	v_pk_mul_f32 v[84:85], v[80:81], v[84:85]
	v_pk_mul_f32 v[94:95], v[90:91], v[94:95]
	v_pk_mul_f32 v[86:87], v[82:83], v[86:87]
	v_pk_mul_f32 v[76:77], v[72:73], v[76:77]
	v_pk_mul_f32 v[68:69], v[64:65], v[68:69]
	v_pk_mul_f32 v[78:79], v[74:75], v[78:79]
	v_pk_mul_f32 v[70:71], v[66:67], v[70:71]
	v_pk_mul_f32 v[60:61], v[56:57], v[60:61]
	v_pk_mul_f32 v[52:53], v[48:49], v[52:53]
	v_pk_mul_f32 v[62:63], v[58:59], v[62:63]
	v_pk_mul_f32 v[54:55], v[50:51], v[54:55]
	v_add_u32_e32 v153, 0x80, v158
	v_pk_mul_f32 v[44:45], v[40:41], v[44:45]
	v_pk_mul_f32 v[36:37], v[32:33], v[36:37]
	v_pk_mul_f32 v[46:47], v[42:43], v[46:47]
	v_pk_mul_f32 v[38:39], v[34:35], v[38:39]
	v_add_u32_e32 v151, 0x90, v158
	v_pk_mul_f32 v[28:29], v[24:25], v[28:29]
	v_pk_mul_f32 v[20:21], v[16:17], v[20:21]
	v_pk_mul_f32 v[30:31], v[26:27], v[30:31]
	v_pk_mul_f32 v[22:23], v[18:19], v[22:23]
	v_add_u32_e32 v145, 0xa0, v158
	v_pk_mul_f32 v[12:13], v[8:9], v[12:13]
	v_pk_mul_f32 v[4:5], v[0:1], v[4:5]
	v_pk_mul_f32 v[14:15], v[10:11], v[14:15]
	v_pk_mul_f32 v[6:7], v[2:3], v[6:7]
	v_add_u32_e32 v141, 0xb0, v158
	s_mov_b64 s[22:23], -1
	s_andn2_b64 vcc, exec, s[6:7]
	s_waitcnt vmcnt(8)
	v_fmamk_f32 v157, v157, 0x3a000000, v239
	v_rsq_f32_e32 v157, v157
	s_nop 0
	v_mul_f32_e32 v162, 0xbfb8aa3b, v157
	v_pk_mul_f32 v[124:125], v[124:125], v[162:163] op_sel_hi:[1,0]
	v_pk_mul_f32 v[116:117], v[116:117], v[162:163] op_sel_hi:[1,0]
	v_exp_f32_e32 v124, v124
	v_exp_f32_e32 v125, v125
	v_exp_f32_e32 v116, v116
	v_exp_f32_e32 v117, v117
	v_mul_f32_e32 v160, v157, v157
	v_pk_add_f32 v[124:125], v[124:125], 1.0 op_sel_hi:[1,0]
	v_pk_mul_f32 v[120:121], v[120:121], v[160:161] op_sel_hi:[1,0]
	v_pk_add_f32 v[116:117], v[116:117], 1.0 op_sel_hi:[1,0]
	v_rcp_f32_e32 v124, v124
	v_rcp_f32_e32 v125, v125
	v_rcp_f32_e32 v116, v116
	v_rcp_f32_e32 v117, v117
	v_pk_mul_f32 v[112:113], v[112:113], v[160:161] op_sel_hi:[1,0]
	v_pk_mul_f32 v[120:121], v[120:121], v[124:125]
	v_pk_mul_f32 v[124:125], v[126:127], v[162:163] op_sel_hi:[1,0]
	v_pk_mul_f32 v[116:117], v[112:113], v[116:117]
	v_pk_mul_f32 v[112:113], v[114:115], v[160:161] op_sel_hi:[1,0]
	v_pk_mul_f32 v[114:115], v[118:119], v[162:163] op_sel_hi:[1,0]
	v_exp_f32_e32 v124, v124
	v_exp_f32_e32 v125, v125
	v_exp_f32_e32 v114, v114
	v_exp_f32_e32 v115, v115
	v_pk_mul_f32 v[122:123], v[122:123], v[160:161] op_sel_hi:[1,0]
	v_pk_add_f32 v[124:125], v[124:125], 1.0 op_sel_hi:[1,0]
	v_pk_add_f32 v[114:115], v[114:115], 1.0 op_sel_hi:[1,0]
	v_rcp_f32_e32 v124, v124
	v_rcp_f32_e32 v125, v125
	v_rcp_f32_e32 v114, v114
	v_rcp_f32_e32 v115, v115
	v_pk_mul_f32 v[122:123], v[122:123], v[124:125]
	v_pk_mul_f32 v[118:119], v[112:113], v[114:115]
	v_cvt_pk_bf16_f32 v112, v120, v121
	v_cvt_pk_bf16_f32 v113, v122, v123
	v_cvt_pk_bf16_f32 v114, v116, v117
	v_cvt_pk_bf16_f32 v115, v118, v119
	v_mad_i64_i32 v[116:117], s[0:1], v158, s95, v[138:139]
	global_store_dwordx4 v[116:117], v[112:115], off
	s_nop 1
	v_fmamk_f32 v112, v159, 0x3a000000, v239
	v_rsq_f32_e32 v112, v112
	s_nop 0
	v_mul_f32_e32 v114, v112, v112
	v_mul_f32_e32 v112, 0xbfb8aa3b, v112
	v_pk_mul_f32 v[108:109], v[108:109], v[112:113] op_sel_hi:[1,0]
	v_pk_mul_f32 v[104:105], v[104:105], v[114:115] op_sel_hi:[1,0]
	v_exp_f32_e32 v108, v108
	v_exp_f32_e32 v109, v109
	v_pk_mul_f32 v[96:97], v[96:97], v[112:113] op_sel_hi:[1,0]
	v_pk_mul_f32 v[98:99], v[98:99], v[112:113] op_sel_hi:[1,0]
	v_exp_f32_e32 v96, v96
	v_pk_add_f32 v[108:109], v[108:109], 1.0 op_sel_hi:[1,0]
	v_exp_f32_e32 v97, v97
	v_rcp_f32_e32 v108, v108
	v_rcp_f32_e32 v109, v109
	v_exp_f32_e32 v98, v98
	v_exp_f32_e32 v99, v99
	v_pk_add_f32 v[96:97], v[96:97], 1.0 op_sel_hi:[1,0]
	v_pk_mul_f32 v[104:105], v[104:105], v[108:109]
	v_pk_mul_f32 v[108:109], v[110:111], v[112:113] op_sel_hi:[1,0]
	v_rcp_f32_e32 v96, v96
	v_exp_f32_e32 v108, v108
	v_exp_f32_e32 v109, v109
	v_rcp_f32_e32 v97, v97
	v_pk_add_f32 v[98:99], v[98:99], 1.0 op_sel_hi:[1,0]
	v_pk_mul_f32 v[100:101], v[100:101], v[114:115] op_sel_hi:[1,0]
	v_pk_add_f32 v[108:109], v[108:109], 1.0 op_sel_hi:[1,0]
	v_rcp_f32_e32 v98, v98
	v_rcp_f32_e32 v108, v108
	v_rcp_f32_e32 v109, v109
	v_rcp_f32_e32 v99, v99
	v_pk_mul_f32 v[106:107], v[106:107], v[114:115] op_sel_hi:[1,0]
	v_pk_mul_f32 v[100:101], v[100:101], v[96:97]
	v_pk_mul_f32 v[96:97], v[102:103], v[114:115] op_sel_hi:[1,0]
	v_pk_mul_f32 v[106:107], v[106:107], v[108:109]
	v_pk_mul_f32 v[102:103], v[96:97], v[98:99]
	v_cvt_pk_bf16_f32 v96, v104, v105
	v_cvt_pk_bf16_f32 v97, v106, v107
	v_cvt_pk_bf16_f32 v98, v100, v101
	v_cvt_pk_bf16_f32 v99, v102, v103
	v_mad_i64_i32 v[100:101], s[0:1], v144, s95, v[138:139]
	global_store_dwordx4 v[100:101], v[96:99], off
	s_nop 1
	v_fmamk_f32 v96, v156, 0x3a000000, v239
	v_rsq_f32_e32 v97, v96
	s_nop 0
	v_mul_f32_e32 v98, 0xbfb8aa3b, v97
	v_pk_mul_f32 v[88:89], v[88:89], v[98:99] op_sel_hi:[1,0]
	v_pk_mul_f32 v[80:81], v[80:81], v[98:99] op_sel_hi:[1,0]
	v_exp_f32_e32 v88, v88
	v_exp_f32_e32 v89, v89
	v_pk_mul_f32 v[90:91], v[90:91], v[98:99] op_sel_hi:[1,0]
	v_exp_f32_e32 v80, v80
	v_exp_f32_e32 v81, v81
	v_pk_mul_f32 v[82:83], v[82:83], v[98:99] op_sel_hi:[1,0]
	v_exp_f32_e32 v90, v90
	v_exp_f32_e32 v91, v91
	v_exp_f32_e32 v82, v82
	v_exp_f32_e32 v83, v83
	v_pk_add_f32 v[88:89], v[88:89], 1.0 op_sel_hi:[1,0]
	v_pk_add_f32 v[80:81], v[80:81], 1.0 op_sel_hi:[1,0]
	v_rcp_f32_e32 v88, v88
	v_rcp_f32_e32 v89, v89
	v_pk_add_f32 v[90:91], v[90:91], 1.0 op_sel_hi:[1,0]
	v_rcp_f32_e32 v80, v80
	v_rcp_f32_e32 v81, v81
	v_pk_add_f32 v[82:83], v[82:83], 1.0 op_sel_hi:[1,0]
	v_rcp_f32_e32 v90, v90
	v_rcp_f32_e32 v91, v91
	v_rcp_f32_e32 v82, v82
	v_rcp_f32_e32 v83, v83
	v_mul_f32_e32 v96, v97, v97
	v_pk_mul_f32 v[92:93], v[92:93], v[96:97] op_sel_hi:[1,0]
	v_pk_mul_f32 v[84:85], v[84:85], v[96:97] op_sel_hi:[1,0]
	v_pk_mul_f32 v[88:89], v[92:93], v[88:89]
	v_pk_mul_f32 v[92:93], v[94:95], v[96:97] op_sel_hi:[1,0]
	v_pk_mul_f32 v[84:85], v[84:85], v[80:81]
	v_pk_mul_f32 v[80:81], v[86:87], v[96:97] op_sel_hi:[1,0]
	v_pk_mul_f32 v[90:91], v[92:93], v[90:91]
	v_pk_mul_f32 v[86:87], v[80:81], v[82:83]
	v_cvt_pk_bf16_f32 v80, v88, v89
	v_cvt_pk_bf16_f32 v81, v90, v91
	v_cvt_pk_bf16_f32 v82, v84, v85
	v_cvt_pk_bf16_f32 v83, v86, v87
	v_mad_i64_i32 v[84:85], s[0:1], v142, s95, v[138:139]
	global_store_dwordx4 v[84:85], v[80:83], off
	s_nop 1
	v_fmamk_f32 v80, v155, 0x3a000000, v239
	v_rsq_f32_e32 v81, v80
	s_nop 0
	v_mul_f32_e32 v82, 0xbfb8aa3b, v81
	v_pk_mul_f32 v[72:73], v[72:73], v[82:83] op_sel_hi:[1,0]
	v_pk_mul_f32 v[64:65], v[64:65], v[82:83] op_sel_hi:[1,0]
	v_exp_f32_e32 v72, v72
	v_exp_f32_e32 v73, v73
	v_pk_mul_f32 v[74:75], v[74:75], v[82:83] op_sel_hi:[1,0]
	v_exp_f32_e32 v64, v64
	v_exp_f32_e32 v65, v65
	v_pk_mul_f32 v[66:67], v[66:67], v[82:83] op_sel_hi:[1,0]
	v_exp_f32_e32 v74, v74
	v_exp_f32_e32 v75, v75
	v_exp_f32_e32 v66, v66
	v_exp_f32_e32 v67, v67
	v_pk_add_f32 v[72:73], v[72:73], 1.0 op_sel_hi:[1,0]
	v_pk_add_f32 v[64:65], v[64:65], 1.0 op_sel_hi:[1,0]
	v_rcp_f32_e32 v72, v72
	v_rcp_f32_e32 v73, v73
	v_pk_add_f32 v[74:75], v[74:75], 1.0 op_sel_hi:[1,0]
	v_rcp_f32_e32 v64, v64
	v_rcp_f32_e32 v65, v65
	v_pk_add_f32 v[66:67], v[66:67], 1.0 op_sel_hi:[1,0]
	v_rcp_f32_e32 v74, v74
	v_rcp_f32_e32 v75, v75
	v_rcp_f32_e32 v66, v66
	v_rcp_f32_e32 v67, v67
	v_mul_f32_e32 v80, v81, v81
	v_pk_mul_f32 v[76:77], v[76:77], v[80:81] op_sel_hi:[1,0]
	v_pk_mul_f32 v[68:69], v[68:69], v[80:81] op_sel_hi:[1,0]
	v_pk_mul_f32 v[72:73], v[76:77], v[72:73]
	v_pk_mul_f32 v[76:77], v[78:79], v[80:81] op_sel_hi:[1,0]
	v_pk_mul_f32 v[68:69], v[68:69], v[64:65]
	v_pk_mul_f32 v[64:65], v[70:71], v[80:81] op_sel_hi:[1,0]
	v_pk_mul_f32 v[74:75], v[76:77], v[74:75]
	v_pk_mul_f32 v[70:71], v[64:65], v[66:67]
	v_cvt_pk_bf16_f32 v64, v72, v73
	v_cvt_pk_bf16_f32 v65, v74, v75
	v_cvt_pk_bf16_f32 v66, v68, v69
	v_cvt_pk_bf16_f32 v67, v70, v71
	v_mad_i64_i32 v[68:69], s[0:1], v140, s95, v[138:139]
	global_store_dwordx4 v[68:69], v[64:67], off
	s_nop 1
	v_fmamk_f32 v64, v154, 0x3a000000, v239
	v_rsq_f32_e32 v65, v64
	s_nop 0
	v_mul_f32_e32 v66, 0xbfb8aa3b, v65
	v_pk_mul_f32 v[56:57], v[56:57], v[66:67] op_sel_hi:[1,0]
	v_pk_mul_f32 v[48:49], v[48:49], v[66:67] op_sel_hi:[1,0]
	v_exp_f32_e32 v56, v56
	v_exp_f32_e32 v57, v57
	v_pk_mul_f32 v[58:59], v[58:59], v[66:67] op_sel_hi:[1,0]
	v_exp_f32_e32 v48, v48
	v_exp_f32_e32 v49, v49
	v_pk_mul_f32 v[50:51], v[50:51], v[66:67] op_sel_hi:[1,0]
	v_exp_f32_e32 v58, v58
	v_exp_f32_e32 v59, v59
	v_exp_f32_e32 v50, v50
	v_exp_f32_e32 v51, v51
	v_pk_add_f32 v[56:57], v[56:57], 1.0 op_sel_hi:[1,0]
	v_pk_add_f32 v[48:49], v[48:49], 1.0 op_sel_hi:[1,0]
	v_rcp_f32_e32 v56, v56
	v_rcp_f32_e32 v57, v57
	v_pk_add_f32 v[58:59], v[58:59], 1.0 op_sel_hi:[1,0]
	v_rcp_f32_e32 v48, v48
	v_rcp_f32_e32 v49, v49
	v_pk_add_f32 v[50:51], v[50:51], 1.0 op_sel_hi:[1,0]
	v_rcp_f32_e32 v58, v58
	v_rcp_f32_e32 v59, v59
	v_rcp_f32_e32 v50, v50
	v_rcp_f32_e32 v51, v51
	v_mul_f32_e32 v64, v65, v65
	v_pk_mul_f32 v[60:61], v[60:61], v[64:65] op_sel_hi:[1,0]
	v_pk_mul_f32 v[52:53], v[52:53], v[64:65] op_sel_hi:[1,0]
	v_pk_mul_f32 v[56:57], v[60:61], v[56:57]
	v_pk_mul_f32 v[60:61], v[62:63], v[64:65] op_sel_hi:[1,0]
	v_pk_mul_f32 v[52:53], v[52:53], v[48:49]
	v_pk_mul_f32 v[48:49], v[54:55], v[64:65] op_sel_hi:[1,0]
	v_pk_mul_f32 v[58:59], v[60:61], v[58:59]
	v_pk_mul_f32 v[54:55], v[48:49], v[50:51]
	v_cvt_pk_bf16_f32 v48, v56, v57
	v_cvt_pk_bf16_f32 v49, v58, v59
	v_cvt_pk_bf16_f32 v50, v52, v53
	v_cvt_pk_bf16_f32 v51, v54, v55
	v_mad_i64_i32 v[52:53], s[0:1], v153, s95, v[138:139]
	global_store_dwordx4 v[52:53], v[48:51], off
	s_nop 1
	v_fmamk_f32 v48, v152, 0x3a000000, v239
	v_rsq_f32_e32 v49, v48
	s_nop 0
	v_mul_f32_e32 v50, 0xbfb8aa3b, v49
	v_pk_mul_f32 v[40:41], v[40:41], v[50:51] op_sel_hi:[1,0]
	v_pk_mul_f32 v[32:33], v[32:33], v[50:51] op_sel_hi:[1,0]
	v_exp_f32_e32 v40, v40
	v_exp_f32_e32 v41, v41
	v_pk_mul_f32 v[42:43], v[42:43], v[50:51] op_sel_hi:[1,0]
	v_exp_f32_e32 v32, v32
	v_exp_f32_e32 v33, v33
	v_pk_mul_f32 v[34:35], v[34:35], v[50:51] op_sel_hi:[1,0]
	v_exp_f32_e32 v42, v42
	v_exp_f32_e32 v43, v43
	v_exp_f32_e32 v34, v34
	v_exp_f32_e32 v35, v35
	v_pk_add_f32 v[40:41], v[40:41], 1.0 op_sel_hi:[1,0]
	v_pk_add_f32 v[32:33], v[32:33], 1.0 op_sel_hi:[1,0]
	v_rcp_f32_e32 v40, v40
	v_rcp_f32_e32 v41, v41
	v_pk_add_f32 v[42:43], v[42:43], 1.0 op_sel_hi:[1,0]
	v_rcp_f32_e32 v32, v32
	v_rcp_f32_e32 v33, v33
	v_pk_add_f32 v[34:35], v[34:35], 1.0 op_sel_hi:[1,0]
	v_rcp_f32_e32 v42, v42
	v_rcp_f32_e32 v43, v43
	v_rcp_f32_e32 v34, v34
	v_rcp_f32_e32 v35, v35
	v_mul_f32_e32 v48, v49, v49
	v_pk_mul_f32 v[44:45], v[44:45], v[48:49] op_sel_hi:[1,0]
	v_pk_mul_f32 v[36:37], v[36:37], v[48:49] op_sel_hi:[1,0]
	v_pk_mul_f32 v[40:41], v[44:45], v[40:41]
	v_pk_mul_f32 v[44:45], v[46:47], v[48:49] op_sel_hi:[1,0]
	v_pk_mul_f32 v[36:37], v[36:37], v[32:33]
	v_pk_mul_f32 v[32:33], v[38:39], v[48:49] op_sel_hi:[1,0]
	v_pk_mul_f32 v[42:43], v[44:45], v[42:43]
	v_pk_mul_f32 v[38:39], v[32:33], v[34:35]
	v_cvt_pk_bf16_f32 v32, v40, v41
	v_cvt_pk_bf16_f32 v33, v42, v43
	v_cvt_pk_bf16_f32 v34, v36, v37
	v_cvt_pk_bf16_f32 v35, v38, v39
	v_mad_i64_i32 v[36:37], s[0:1], v151, s95, v[138:139]
	global_store_dwordx4 v[36:37], v[32:35], off
	s_nop 1
	v_fmamk_f32 v32, v150, 0x3a000000, v239
	v_rsq_f32_e32 v33, v32
	s_nop 0
	v_mul_f32_e32 v34, 0xbfb8aa3b, v33
	v_pk_mul_f32 v[24:25], v[24:25], v[34:35] op_sel_hi:[1,0]
	v_pk_mul_f32 v[16:17], v[16:17], v[34:35] op_sel_hi:[1,0]
	v_exp_f32_e32 v24, v24
	v_exp_f32_e32 v25, v25
	v_pk_mul_f32 v[26:27], v[26:27], v[34:35] op_sel_hi:[1,0]
	v_exp_f32_e32 v16, v16
	v_exp_f32_e32 v17, v17
	v_pk_mul_f32 v[18:19], v[18:19], v[34:35] op_sel_hi:[1,0]
	v_exp_f32_e32 v26, v26
	v_exp_f32_e32 v27, v27
	v_exp_f32_e32 v18, v18
	v_exp_f32_e32 v19, v19
	v_pk_add_f32 v[24:25], v[24:25], 1.0 op_sel_hi:[1,0]
	v_pk_add_f32 v[16:17], v[16:17], 1.0 op_sel_hi:[1,0]
	v_rcp_f32_e32 v24, v24
	v_rcp_f32_e32 v25, v25
	v_pk_add_f32 v[26:27], v[26:27], 1.0 op_sel_hi:[1,0]
	v_rcp_f32_e32 v16, v16
	v_rcp_f32_e32 v17, v17
	v_pk_add_f32 v[18:19], v[18:19], 1.0 op_sel_hi:[1,0]
	v_rcp_f32_e32 v26, v26
	v_rcp_f32_e32 v27, v27
	v_rcp_f32_e32 v18, v18
	v_rcp_f32_e32 v19, v19
	v_mul_f32_e32 v32, v33, v33
	v_pk_mul_f32 v[28:29], v[28:29], v[32:33] op_sel_hi:[1,0]
	v_pk_mul_f32 v[20:21], v[20:21], v[32:33] op_sel_hi:[1,0]
	v_pk_mul_f32 v[24:25], v[28:29], v[24:25]
	v_pk_mul_f32 v[28:29], v[30:31], v[32:33] op_sel_hi:[1,0]
	v_pk_mul_f32 v[20:21], v[20:21], v[16:17]
	v_pk_mul_f32 v[16:17], v[22:23], v[32:33] op_sel_hi:[1,0]
	v_pk_mul_f32 v[26:27], v[28:29], v[26:27]
	v_pk_mul_f32 v[22:23], v[16:17], v[18:19]
	v_cvt_pk_bf16_f32 v16, v24, v25
	v_cvt_pk_bf16_f32 v17, v26, v27
	v_cvt_pk_bf16_f32 v18, v20, v21
	v_cvt_pk_bf16_f32 v19, v22, v23
	v_mad_i64_i32 v[20:21], s[0:1], v145, s95, v[138:139]
	global_store_dwordx4 v[20:21], v[16:19], off
	s_nop 1
	v_fmamk_f32 v16, v143, 0x3a000000, v239
	v_rsq_f32_e32 v17, v16
	s_nop 0
	v_mul_f32_e32 v18, 0xbfb8aa3b, v17
	v_pk_mul_f32 v[8:9], v[8:9], v[18:19] op_sel_hi:[1,0]
	v_pk_mul_f32 v[0:1], v[0:1], v[18:19] op_sel_hi:[1,0]
	v_exp_f32_e32 v8, v8
	v_exp_f32_e32 v9, v9
	v_pk_mul_f32 v[10:11], v[10:11], v[18:19] op_sel_hi:[1,0]
	v_exp_f32_e32 v0, v0
	v_exp_f32_e32 v1, v1
	v_pk_mul_f32 v[2:3], v[2:3], v[18:19] op_sel_hi:[1,0]
	v_exp_f32_e32 v10, v10
	v_exp_f32_e32 v11, v11
	v_exp_f32_e32 v2, v2
	v_exp_f32_e32 v3, v3
	v_pk_add_f32 v[8:9], v[8:9], 1.0 op_sel_hi:[1,0]
	v_pk_add_f32 v[0:1], v[0:1], 1.0 op_sel_hi:[1,0]
	v_rcp_f32_e32 v8, v8
	v_rcp_f32_e32 v9, v9
	v_pk_add_f32 v[10:11], v[10:11], 1.0 op_sel_hi:[1,0]
	v_rcp_f32_e32 v0, v0
	v_rcp_f32_e32 v1, v1
	v_pk_add_f32 v[2:3], v[2:3], 1.0 op_sel_hi:[1,0]
	v_rcp_f32_e32 v10, v10
	v_rcp_f32_e32 v11, v11
	v_rcp_f32_e32 v2, v2
	v_rcp_f32_e32 v3, v3
	v_mul_f32_e32 v16, v17, v17
	v_pk_mul_f32 v[12:13], v[12:13], v[16:17] op_sel_hi:[1,0]
	v_pk_mul_f32 v[4:5], v[4:5], v[16:17] op_sel_hi:[1,0]
	v_pk_mul_f32 v[8:9], v[12:13], v[8:9]
	v_pk_mul_f32 v[12:13], v[14:15], v[16:17] op_sel_hi:[1,0]
	v_pk_mul_f32 v[4:5], v[4:5], v[0:1]
	v_pk_mul_f32 v[0:1], v[6:7], v[16:17] op_sel_hi:[1,0]
	v_pk_mul_f32 v[10:11], v[12:13], v[10:11]
	v_pk_mul_f32 v[6:7], v[0:1], v[2:3]
	v_cvt_pk_bf16_f32 v0, v8, v9
	v_cvt_pk_bf16_f32 v1, v10, v11
	v_cvt_pk_bf16_f32 v2, v4, v5
	v_cvt_pk_bf16_f32 v3, v6, v7
	v_mad_i64_i32 v[4:5], s[0:1], v141, s95, v[138:139]
	global_store_dwordx4 v[4:5], v[0:3], off
	s_waitcnt vmcnt(8)
	s_cbranch_vccnz .LBB0_99
	s_andn2_b64 vcc, exec, s[8:9]
	s_cbranch_vccnz .LBB0_98
	s_barrier
	s_branch .LBB0_98

.LBB0_527:
	v_lshl_add_u32 v248, s28, 8, v146
	v_lshlrev_b32_e32 v248, 2, v248
	global_load_dword v230, v248, s[72:73]
	global_load_dword v231, v248, s[72:73] offset:64
	global_load_dword v232, v248, s[72:73] offset:128
	global_load_dword v233, v248, s[72:73] offset:192
	global_load_dword v234, v248, s[72:73] offset:512
	global_load_dword v235, v248, s[72:73] offset:576
	global_load_dword v236, v248, s[72:73] offset:640
	global_load_dword v237, v248, s[72:73] offset:704
	s_ashr_i32 s17, s16, 31
	s_lshl_b64 s[0:1], s[16:17], 20
	s_add_u32 s18, s26, s0
	s_addc_u32 s19, s27, s1
	s_and_b64 s[0:1], s[6:7], exec
	s_cselect_b32 s17, s19, s31
	s_cselect_b32 s51, s18, s30
	s_ashr_i32 s15, s14, 31
	s_lshl_b64 s[0:1], s[14:15], 20
	s_add_u32 s20, s70, s0
	s_addc_u32 s21, s71, s1
	s_and_b64 s[0:1], s[6:7], exec
	s_cselect_b32 s15, s21, s37
	s_cselect_b32 s34, s20, s36
	s_add_u32 s30, s30, 0x80080
	s_addc_u32 s31, s31, 0
	s_add_u32 s35, s36, 0x100
	s_addc_u32 s52, s37, 0
	s_mov_b32 s61, -2
	s_add_u32 s0, s30, 0xfff80080
	s_addc_u32 s1, s31, -1
	s_add_i32 s59, 0, 0x10000
	s_cmp_eq_u32 s61, 28
	s_cselect_b32 s39, s17, s1
	s_cselect_b32 s38, s51, s0
	s_cselect_b32 s37, s15, s52
	s_cselect_b32 s36, s34, s35
	s_add_i32 s63, 0, 0x14000
	v_add_u32_e32 v154, s59, v147
	v_add_u32_e32 v170, s63, v147
	ds_read_b128 v[138:141], v154
	ds_read_b128 v[142:145], v154 offset:1024
	ds_read_b128 v[150:153], v154 offset:2048
	ds_read_b128 v[154:157], v154 offset:3072
	ds_read_b128 v[158:161], v170
	ds_read_b128 v[162:165], v170 offset:1024
	ds_read_b128 v[166:169], v170 offset:2048
	ds_read_b128 v[170:173], v170 offset:3072
	v_lshl_add_u64 v[220:221], s[30:31], 0, v[134:135]
	s_add_i32 m0, s42, 0xc000
	ds_read_b128 v[174:177], v149
	ds_read_b128 v[178:181], v149 offset:1024
	ds_read_b128 v[182:185], v149 offset:2048
	ds_read_b128 v[186:189], v149 offset:3072
	ds_read_b128 v[190:193], v149 offset:4096
	ds_read_b128 v[194:197], v149 offset:5120
	ds_read_b128 v[212:215], v149 offset:6144
	ds_read_b128 v[216:219], v149 offset:7168
	global_load_lds_dwordx4 v[220:221], off
	v_lshl_add_u64 v[220:221], s[30:31], 0, v[136:137]
	s_add_i32 m0, s42, 0xe000
	s_nop 0
	global_load_lds_dwordx4 v[220:221], off
	s_waitcnt vmcnt(63)
	s_waitcnt lgkmcnt(0)
	s_barrier
	s_setprio 1
	s_waitcnt lgkmcnt(0)
	v_mfma_f32_16x16x32_bf16 v[124:127], v[138:141], v[174:177], 0
	v_mfma_f32_16x16x32_bf16 v[116:119], v[150:153], v[174:177], 0
	v_mfma_f32_16x16x32_bf16 v[108:111], v[138:141], v[182:185], 0
	v_mfma_f32_16x16x32_bf16 v[96:99], v[150:153], v[182:185], 0
	v_mfma_f32_16x16x32_bf16 v[88:91], v[138:141], v[190:193], 0
	v_mfma_f32_16x16x32_bf16 v[80:83], v[150:153], v[190:193], 0
	v_mfma_f32_16x16x32_bf16 v[72:75], v[138:141], v[212:215], 0
	v_mfma_f32_16x16x32_bf16 v[64:67], v[150:153], v[212:215], 0
	v_mfma_f32_16x16x32_bf16 v[124:127], v[142:145], v[178:181], v[124:127]
	v_mfma_f32_16x16x32_bf16 v[116:119], v[154:157], v[178:181], v[116:119]
	v_mfma_f32_16x16x32_bf16 v[108:111], v[142:145], v[186:189], v[108:111]
	v_mfma_f32_16x16x32_bf16 v[96:99], v[154:157], v[186:189], v[96:99]
	v_mfma_f32_16x16x32_bf16 v[88:91], v[142:145], v[194:197], v[88:91]
	v_mfma_f32_16x16x32_bf16 v[80:83], v[154:157], v[194:197], v[80:83]
	v_mfma_f32_16x16x32_bf16 v[72:75], v[142:145], v[216:219], v[72:75]
	v_mfma_f32_16x16x32_bf16 v[64:67], v[154:157], v[216:219], v[64:67]
	s_setprio 0
	s_setprio 1
	v_mfma_f32_16x16x32_bf16 v[120:123], v[158:161], v[174:177], 0
	v_mfma_f32_16x16x32_bf16 v[112:115], v[166:169], v[174:177], 0
	v_mfma_f32_16x16x32_bf16 v[104:107], v[158:161], v[182:185], 0
	v_mfma_f32_16x16x32_bf16 v[100:103], v[166:169], v[182:185], 0
	v_mfma_f32_16x16x32_bf16 v[92:95], v[158:161], v[190:193], 0
	v_mfma_f32_16x16x32_bf16 v[84:87], v[166:169], v[190:193], 0
	v_mfma_f32_16x16x32_bf16 v[76:79], v[158:161], v[212:215], 0
	v_mfma_f32_16x16x32_bf16 v[68:71], v[166:169], v[212:215], 0
	v_mfma_f32_16x16x32_bf16 v[120:123], v[162:165], v[178:181], v[120:123]
	v_mfma_f32_16x16x32_bf16 v[112:115], v[170:173], v[178:181], v[112:115]
	v_mfma_f32_16x16x32_bf16 v[104:107], v[162:165], v[186:189], v[104:107]
	v_mfma_f32_16x16x32_bf16 v[100:103], v[170:173], v[186:189], v[100:103]
	v_mfma_f32_16x16x32_bf16 v[92:95], v[162:165], v[194:197], v[92:95]
	v_mfma_f32_16x16x32_bf16 v[84:87], v[170:173], v[194:197], v[84:87]
	v_mfma_f32_16x16x32_bf16 v[76:79], v[162:165], v[216:219], v[76:79]
	v_mfma_f32_16x16x32_bf16 v[68:71], v[170:173], v[216:219], v[68:71]
	s_setprio 0
	s_barrier
	s_add_i32 s0, s59, s40
	v_lshl_add_u64 v[220:221], s[36:37], 0, v[198:199]
	s_mov_b32 m0, s0
	ds_read_b128 v[174:177], v149 offset:16384
	ds_read_b128 v[178:181], v149 offset:17408
	ds_read_b128 v[182:185], v149 offset:18432
	ds_read_b128 v[186:189], v149 offset:19456
	ds_read_b128 v[190:193], v149 offset:20480
	ds_read_b128 v[194:197], v149 offset:21504
	ds_read_b128 v[212:215], v149 offset:22528
	ds_read_b128 v[216:219], v149 offset:23552
	global_load_lds_dwordx4 v[220:221], off
	s_add_i32 m0, s0, 0x2000
	s_add_u32 s0, s36, 0x80000
	v_lshl_add_u64 v[222:223], s[36:37], 0, v[128:129]
	s_addc_u32 s1, s37, 0
	s_add_i32 s59, s63, s40
	global_load_lds_dwordx4 v[222:223], off
	v_lshl_add_u64 v[224:225], s[0:1], 0, v[198:199]
	s_mov_b32 m0, s59
	v_lshl_add_u64 v[226:227], s[38:39], 0, v[130:131]
	global_load_lds_dwordx4 v[224:225], off
	v_lshl_add_u64 v[224:225], s[0:1], 0, v[128:129]
	s_add_i32 m0, s59, 0x2000
	s_nop 0
	global_load_lds_dwordx4 v[224:225], off
	v_lshl_add_u64 v[224:225], s[38:39], 0, v[132:133]
	s_mov_b32 m0, s42
	s_nop 0
	global_load_lds_dwordx4 v[224:225], off
	s_mov_b32 m0, s43
	s_nop 0
	global_load_lds_dwordx4 v[226:227], off
	s_waitcnt vmcnt(63)
	s_waitcnt lgkmcnt(0)
	s_barrier
	s_setprio 1
	s_waitcnt lgkmcnt(0)
	v_mfma_f32_16x16x32_bf16 v[56:59], v[138:141], v[174:177], 0
	v_mfma_f32_16x16x32_bf16 v[48:51], v[150:153], v[174:177], 0
	v_mfma_f32_16x16x32_bf16 v[40:43], v[138:141], v[182:185], 0
	v_mfma_f32_16x16x32_bf16 v[32:35], v[150:153], v[182:185], 0
	v_mfma_f32_16x16x32_bf16 v[24:27], v[138:141], v[190:193], 0
	v_mfma_f32_16x16x32_bf16 v[16:19], v[150:153], v[190:193], 0
	v_mfma_f32_16x16x32_bf16 v[8:11], v[138:141], v[212:215], 0
	v_mfma_f32_16x16x32_bf16 v[0:3], v[150:153], v[212:215], 0
	v_mfma_f32_16x16x32_bf16 v[56:59], v[142:145], v[178:181], v[56:59]
	v_mfma_f32_16x16x32_bf16 v[48:51], v[154:157], v[178:181], v[48:51]
	v_mfma_f32_16x16x32_bf16 v[40:43], v[142:145], v[186:189], v[40:43]
	v_mfma_f32_16x16x32_bf16 v[32:35], v[154:157], v[186:189], v[32:35]
	v_mfma_f32_16x16x32_bf16 v[24:27], v[142:145], v[194:197], v[24:27]
	v_mfma_f32_16x16x32_bf16 v[16:19], v[154:157], v[194:197], v[16:19]
	v_mfma_f32_16x16x32_bf16 v[8:11], v[142:145], v[216:219], v[8:11]
	v_mfma_f32_16x16x32_bf16 v[0:3], v[154:157], v[216:219], v[0:3]
	s_setprio 0
	s_setprio 1
	v_mfma_f32_16x16x32_bf16 v[60:63], v[158:161], v[174:177], 0
	v_mfma_f32_16x16x32_bf16 v[52:55], v[166:169], v[174:177], 0
	v_mfma_f32_16x16x32_bf16 v[44:47], v[158:161], v[182:185], 0
	v_mfma_f32_16x16x32_bf16 v[36:39], v[166:169], v[182:185], 0
	v_mfma_f32_16x16x32_bf16 v[28:31], v[158:161], v[190:193], 0
	v_mfma_f32_16x16x32_bf16 v[20:23], v[166:169], v[190:193], 0
	v_mfma_f32_16x16x32_bf16 v[12:15], v[158:161], v[212:215], 0
	v_mfma_f32_16x16x32_bf16 v[4:7], v[166:169], v[212:215], 0
	v_mfma_f32_16x16x32_bf16 v[60:63], v[162:165], v[178:181], v[60:63]
	v_mfma_f32_16x16x32_bf16 v[52:55], v[170:173], v[178:181], v[52:55]
	v_mfma_f32_16x16x32_bf16 v[44:47], v[162:165], v[186:189], v[44:47]
	v_mfma_f32_16x16x32_bf16 v[36:39], v[170:173], v[186:189], v[36:39]
	v_mfma_f32_16x16x32_bf16 v[28:31], v[162:165], v[194:197], v[28:31]
	v_mfma_f32_16x16x32_bf16 v[20:23], v[170:173], v[194:197], v[20:23]
	v_mfma_f32_16x16x32_bf16 v[12:15], v[162:165], v[216:219], v[12:15]
	v_mfma_f32_16x16x32_bf16 v[4:7], v[170:173], v[216:219], v[4:7]
	s_setprio 0
	s_barrier
	s_add_i32 s59, 0, 0x18000
	s_add_i32 s63, 0, 0x1c000
	v_add_u32_e32 v154, s59, v147
	v_add_u32_e32 v170, s63, v147
	ds_read_b128 v[138:141], v154
	ds_read_b128 v[142:145], v154 offset:1024
	ds_read_b128 v[150:153], v154 offset:2048
	ds_read_b128 v[154:157], v154 offset:3072
	ds_read_b128 v[158:161], v170
	ds_read_b128 v[162:165], v170 offset:1024
	ds_read_b128 v[166:169], v170 offset:2048
	ds_read_b128 v[170:173], v170 offset:3072
	s_add_u32 s0, s38, 0x80000
	s_addc_u32 s1, s39, 0
	s_mov_b32 m0, s44
	v_lshl_add_u64 v[228:229], s[0:1], 0, v[132:133]
	ds_read_b128 v[174:177], v149 offset:32768
	ds_read_b128 v[178:181], v149 offset:33792
	ds_read_b128 v[182:185], v149 offset:34816
	ds_read_b128 v[186:189], v149 offset:35840
	ds_read_b128 v[190:193], v149 offset:36864
	ds_read_b128 v[194:197], v149 offset:37888
	ds_read_b128 v[212:215], v149 offset:38912
	ds_read_b128 v[216:219], v149 offset:39936
	global_load_lds_dwordx4 v[228:229], off
	v_lshl_add_u64 v[228:229], s[0:1], 0, v[130:131]
	s_mov_b32 m0, s45
	s_nop 0
	global_load_lds_dwordx4 v[228:229], off
	s_waitcnt vmcnt(8)
	s_waitcnt lgkmcnt(0)
	s_barrier
	s_setprio 1
	s_waitcnt lgkmcnt(0)
	v_mfma_f32_16x16x32_bf16 v[124:127], v[138:141], v[174:177], v[124:127]
	v_mfma_f32_16x16x32_bf16 v[116:119], v[150:153], v[174:177], v[116:119]
	v_mfma_f32_16x16x32_bf16 v[108:111], v[138:141], v[182:185], v[108:111]
	v_mfma_f32_16x16x32_bf16 v[96:99], v[150:153], v[182:185], v[96:99]
	v_mfma_f32_16x16x32_bf16 v[88:91], v[138:141], v[190:193], v[88:91]
	v_mfma_f32_16x16x32_bf16 v[80:83], v[150:153], v[190:193], v[80:83]
	v_mfma_f32_16x16x32_bf16 v[72:75], v[138:141], v[212:215], v[72:75]
	v_mfma_f32_16x16x32_bf16 v[64:67], v[150:153], v[212:215], v[64:67]
	v_mfma_f32_16x16x32_bf16 v[124:127], v[142:145], v[178:181], v[124:127]
	v_mfma_f32_16x16x32_bf16 v[116:119], v[154:157], v[178:181], v[116:119]
	v_mfma_f32_16x16x32_bf16 v[108:111], v[142:145], v[186:189], v[108:111]
	v_mfma_f32_16x16x32_bf16 v[96:99], v[154:157], v[186:189], v[96:99]
	v_mfma_f32_16x16x32_bf16 v[88:91], v[142:145], v[194:197], v[88:91]
	v_mfma_f32_16x16x32_bf16 v[80:83], v[154:157], v[194:197], v[80:83]
	v_mfma_f32_16x16x32_bf16 v[72:75], v[142:145], v[216:219], v[72:75]
	v_mfma_f32_16x16x32_bf16 v[64:67], v[154:157], v[216:219], v[64:67]
	s_setprio 0
	s_setprio 1
	v_mfma_f32_16x16x32_bf16 v[120:123], v[158:161], v[174:177], v[120:123]
	v_mfma_f32_16x16x32_bf16 v[112:115], v[166:169], v[174:177], v[112:115]
	v_mfma_f32_16x16x32_bf16 v[104:107], v[158:161], v[182:185], v[104:107]
	v_mfma_f32_16x16x32_bf16 v[100:103], v[166:169], v[182:185], v[100:103]
	v_mfma_f32_16x16x32_bf16 v[92:95], v[158:161], v[190:193], v[92:95]
	v_mfma_f32_16x16x32_bf16 v[84:87], v[166:169], v[190:193], v[84:87]
	v_mfma_f32_16x16x32_bf16 v[76:79], v[158:161], v[212:215], v[76:79]
	v_mfma_f32_16x16x32_bf16 v[68:71], v[166:169], v[212:215], v[68:71]
	v_mfma_f32_16x16x32_bf16 v[120:123], v[162:165], v[178:181], v[120:123]
	v_mfma_f32_16x16x32_bf16 v[112:115], v[170:173], v[178:181], v[112:115]
	v_mfma_f32_16x16x32_bf16 v[104:107], v[162:165], v[186:189], v[104:107]
	v_mfma_f32_16x16x32_bf16 v[100:103], v[170:173], v[186:189], v[100:103]
	v_mfma_f32_16x16x32_bf16 v[92:95], v[162:165], v[194:197], v[92:95]
	v_mfma_f32_16x16x32_bf16 v[84:87], v[170:173], v[194:197], v[84:87]
	v_mfma_f32_16x16x32_bf16 v[76:79], v[162:165], v[216:219], v[76:79]
	v_mfma_f32_16x16x32_bf16 v[68:71], v[170:173], v[216:219], v[68:71]
	s_setprio 0
	s_barrier
	s_add_i32 s0, s59, s40
	v_lshl_add_u64 v[220:221], v[220:221], 0, s[54:55]
	s_mov_b32 m0, s0
	ds_read_b128 v[174:177], v149 offset:49152
	ds_read_b128 v[178:181], v149 offset:50176
	ds_read_b128 v[182:185], v149 offset:51200
	ds_read_b128 v[186:189], v149 offset:52224
	ds_read_b128 v[190:193], v149 offset:53248
	ds_read_b128 v[194:197], v149 offset:54272
	ds_read_b128 v[212:215], v149 offset:55296
	ds_read_b128 v[216:219], v149 offset:56320
	global_load_lds_dwordx4 v[220:221], off
	s_add_i32 m0, s0, 0x2000
	s_add_u32 s0, s36, 0x80080
	v_lshl_add_u64 v[220:221], v[222:223], 0, s[54:55]
	s_addc_u32 s1, s37, 0
	s_add_i32 s36, s63, s40
	global_load_lds_dwordx4 v[220:221], off
	v_lshl_add_u64 v[220:221], s[0:1], 0, v[198:199]
	s_mov_b32 m0, s36
	s_nop 0
	global_load_lds_dwordx4 v[220:221], off
	v_lshl_add_u64 v[220:221], s[0:1], 0, v[128:129]
	s_add_i32 m0, s36, 0x2000
	s_nop 0
	global_load_lds_dwordx4 v[220:221], off
	v_lshl_add_u64 v[220:221], v[224:225], 0, s[54:55]
	s_mov_b32 m0, s47
	s_nop 0
	global_load_lds_dwordx4 v[220:221], off
	v_lshl_add_u64 v[220:221], v[226:227], 0, s[54:55]
	s_mov_b32 m0, s48
	s_nop 0
	global_load_lds_dwordx4 v[220:221], off
	s_waitcnt vmcnt(8)
	s_waitcnt lgkmcnt(0)
	s_barrier
	s_setprio 1
	s_waitcnt lgkmcnt(0)
	v_mfma_f32_16x16x32_bf16 v[56:59], v[138:141], v[174:177], v[56:59]
	v_mfma_f32_16x16x32_bf16 v[48:51], v[150:153], v[174:177], v[48:51]
	v_mfma_f32_16x16x32_bf16 v[40:43], v[138:141], v[182:185], v[40:43]
	v_mfma_f32_16x16x32_bf16 v[32:35], v[150:153], v[182:185], v[32:35]
	v_mfma_f32_16x16x32_bf16 v[24:27], v[138:141], v[190:193], v[24:27]
	v_mfma_f32_16x16x32_bf16 v[16:19], v[150:153], v[190:193], v[16:19]
	v_mfma_f32_16x16x32_bf16 v[8:11], v[138:141], v[212:215], v[8:11]
	v_mfma_f32_16x16x32_bf16 v[0:3], v[150:153], v[212:215], v[0:3]
	v_mfma_f32_16x16x32_bf16 v[56:59], v[142:145], v[178:181], v[56:59]
	v_mfma_f32_16x16x32_bf16 v[48:51], v[154:157], v[178:181], v[48:51]
	v_mfma_f32_16x16x32_bf16 v[40:43], v[142:145], v[186:189], v[40:43]
	v_mfma_f32_16x16x32_bf16 v[32:35], v[154:157], v[186:189], v[32:35]
	v_mfma_f32_16x16x32_bf16 v[24:27], v[142:145], v[194:197], v[24:27]
	v_mfma_f32_16x16x32_bf16 v[16:19], v[154:157], v[194:197], v[16:19]
	v_mfma_f32_16x16x32_bf16 v[8:11], v[142:145], v[216:219], v[8:11]
	v_mfma_f32_16x16x32_bf16 v[0:3], v[154:157], v[216:219], v[0:3]
	s_setprio 0
	s_setprio 1
	v_mfma_f32_16x16x32_bf16 v[60:63], v[158:161], v[174:177], v[60:63]
	v_mfma_f32_16x16x32_bf16 v[52:55], v[166:169], v[174:177], v[52:55]
	v_mfma_f32_16x16x32_bf16 v[44:47], v[158:161], v[182:185], v[44:47]
	v_mfma_f32_16x16x32_bf16 v[36:39], v[166:169], v[182:185], v[36:39]
	v_mfma_f32_16x16x32_bf16 v[28:31], v[158:161], v[190:193], v[28:31]
	v_mfma_f32_16x16x32_bf16 v[20:23], v[166:169], v[190:193], v[20:23]
	v_mfma_f32_16x16x32_bf16 v[12:15], v[158:161], v[212:215], v[12:15]
	v_mfma_f32_16x16x32_bf16 v[4:7], v[166:169], v[212:215], v[4:7]
	v_mfma_f32_16x16x32_bf16 v[60:63], v[162:165], v[178:181], v[60:63]
	v_mfma_f32_16x16x32_bf16 v[52:55], v[170:173], v[178:181], v[52:55]
	v_mfma_f32_16x16x32_bf16 v[44:47], v[162:165], v[186:189], v[44:47]
	v_mfma_f32_16x16x32_bf16 v[36:39], v[170:173], v[186:189], v[36:39]
	v_mfma_f32_16x16x32_bf16 v[28:31], v[162:165], v[194:197], v[28:31]
	v_mfma_f32_16x16x32_bf16 v[20:23], v[170:173], v[194:197], v[20:23]
	v_mfma_f32_16x16x32_bf16 v[12:15], v[162:165], v[216:219], v[12:15]
	v_mfma_f32_16x16x32_bf16 v[4:7], v[170:173], v[216:219], v[4:7]
	s_setprio 0
	s_barrier
	s_add_i32 s61, s61, 2
	s_add_u32 s30, s30, 0x100
	s_addc_u32 s31, s31, 0
	s_add_u32 s35, s35, 0x100
	s_addc_u32 s52, s52, 0

.LBB0_531:
	v_lshl_add_u32 v158, s28, 8, v146
	v_ashrrev_i32_e32 v159, 31, v158
	v_lshl_add_u64 v[138:139], v[158:159], 2, s[72:73]
	v_mov_b32_e32 v157, v230
	v_mov_b32_e32 v154, v234
	v_mov_b32_e32 v152, v235
	v_or_b32_e32 v144, 16, v158
	v_ashrrev_i32_e32 v145, 31, v144
	v_lshl_add_u64 v[140:141], v[144:145], 2, s[72:73]
	v_mov_b32_e32 v159, v231
	v_or_b32_e32 v142, 32, v158
	v_ashrrev_i32_e32 v143, 31, v142
	v_lshl_add_u64 v[140:141], v[142:143], 2, s[72:73]
	v_mov_b32_e32 v156, v232
	v_or_b32_e32 v140, 48, v158
	v_ashrrev_i32_e32 v141, 31, v140
	v_lshl_add_u64 v[150:151], v[140:141], 2, s[72:73]
	v_mov_b32_e32 v155, v233
	v_mov_b32_e32 v143, v237
	v_pk_mul_f32 v[120:121], v[124:125], v[120:121]
	v_mov_b32_e32 v150, v236
	v_pk_mul_f32 v[112:113], v[116:117], v[112:113]
	v_pk_mul_f32 v[114:115], v[118:119], v[114:115]
	v_lshl_or_b32 v138, s29, 7, v148
	v_pk_mul_f32 v[122:123], v[126:127], v[122:123]
	v_ashrrev_i32_e32 v139, 31, v138
	v_lshl_add_u64 v[138:139], v[138:139], 1, s[10:11]
	v_pk_mul_f32 v[104:105], v[108:109], v[104:105]
	v_pk_mul_f32 v[100:101], v[96:97], v[100:101]
	v_pk_mul_f32 v[102:103], v[98:99], v[102:103]
	v_pk_mul_f32 v[106:107], v[110:111], v[106:107]
	v_pk_mul_f32 v[92:93], v[88:89], v[92:93]
	v_pk_mul_f32 v[84:85], v[80:81], v[84:85]
	v_pk_mul_f32 v[94:95], v[90:91], v[94:95]
	v_pk_mul_f32 v[86:87], v[82:83], v[86:87]
	v_pk_mul_f32 v[76:77], v[72:73], v[76:77]
	v_pk_mul_f32 v[68:69], v[64:65], v[68:69]
	v_pk_mul_f32 v[78:79], v[74:75], v[78:79]
	v_pk_mul_f32 v[70:71], v[66:67], v[70:71]
	v_pk_mul_f32 v[60:61], v[56:57], v[60:61]
	v_pk_mul_f32 v[52:53], v[48:49], v[52:53]
	v_pk_mul_f32 v[62:63], v[58:59], v[62:63]
	v_pk_mul_f32 v[54:55], v[50:51], v[54:55]
	v_add_u32_e32 v153, 0x80, v158
	v_pk_mul_f32 v[44:45], v[40:41], v[44:45]
	v_pk_mul_f32 v[36:37], v[32:33], v[36:37]
	v_pk_mul_f32 v[46:47], v[42:43], v[46:47]
	v_pk_mul_f32 v[38:39], v[34:35], v[38:39]
	v_add_u32_e32 v151, 0x90, v158
	v_pk_mul_f32 v[28:29], v[24:25], v[28:29]
	v_pk_mul_f32 v[20:21], v[16:17], v[20:21]
	v_pk_mul_f32 v[30:31], v[26:27], v[30:31]
	v_pk_mul_f32 v[22:23], v[18:19], v[22:23]
	v_add_u32_e32 v145, 0xa0, v158
	v_pk_mul_f32 v[12:13], v[8:9], v[12:13]
	v_pk_mul_f32 v[4:5], v[0:1], v[4:5]
	v_pk_mul_f32 v[14:15], v[10:11], v[14:15]
	v_pk_mul_f32 v[6:7], v[2:3], v[6:7]
	v_add_u32_e32 v141, 0xb0, v158
	s_mov_b64 s[28:29], -1
	s_andn2_b64 vcc, exec, s[6:7]
	s_waitcnt vmcnt(8)
	v_fmamk_f32 v157, v157, 0x3a000000, v239
	v_rsq_f32_e32 v157, v157
	s_nop 0
	v_mul_f32_e32 v162, 0xbfb8aa3b, v157
	v_pk_mul_f32 v[124:125], v[124:125], v[162:163] op_sel_hi:[1,0]
	v_pk_mul_f32 v[116:117], v[116:117], v[162:163] op_sel_hi:[1,0]
	v_exp_f32_e32 v124, v124
	v_exp_f32_e32 v125, v125
	v_exp_f32_e32 v116, v116
	v_exp_f32_e32 v117, v117
	v_mul_f32_e32 v160, v157, v157
	v_pk_add_f32 v[124:125], v[124:125], 1.0 op_sel_hi:[1,0]
	v_pk_mul_f32 v[120:121], v[120:121], v[160:161] op_sel_hi:[1,0]
	v_pk_add_f32 v[116:117], v[116:117], 1.0 op_sel_hi:[1,0]
	v_rcp_f32_e32 v124, v124
	v_rcp_f32_e32 v125, v125
	v_rcp_f32_e32 v116, v116
	v_rcp_f32_e32 v117, v117
	v_pk_mul_f32 v[112:113], v[112:113], v[160:161] op_sel_hi:[1,0]
	v_pk_mul_f32 v[120:121], v[120:121], v[124:125]
	v_pk_mul_f32 v[124:125], v[126:127], v[162:163] op_sel_hi:[1,0]
	v_pk_mul_f32 v[116:117], v[112:113], v[116:117]
	v_pk_mul_f32 v[112:113], v[114:115], v[160:161] op_sel_hi:[1,0]
	v_pk_mul_f32 v[114:115], v[118:119], v[162:163] op_sel_hi:[1,0]
	v_exp_f32_e32 v124, v124
	v_exp_f32_e32 v125, v125
	v_exp_f32_e32 v114, v114
	v_exp_f32_e32 v115, v115
	v_pk_mul_f32 v[122:123], v[122:123], v[160:161] op_sel_hi:[1,0]
	v_pk_add_f32 v[124:125], v[124:125], 1.0 op_sel_hi:[1,0]
	v_pk_add_f32 v[114:115], v[114:115], 1.0 op_sel_hi:[1,0]
	v_rcp_f32_e32 v124, v124
	v_rcp_f32_e32 v125, v125
	v_rcp_f32_e32 v114, v114
	v_rcp_f32_e32 v115, v115
	v_pk_mul_f32 v[122:123], v[122:123], v[124:125]
	v_pk_mul_f32 v[118:119], v[112:113], v[114:115]
	v_cvt_pk_bf16_f32 v112, v120, v121
	v_cvt_pk_bf16_f32 v113, v122, v123
	v_cvt_pk_bf16_f32 v114, v116, v117
	v_cvt_pk_bf16_f32 v115, v118, v119
	v_mad_i64_i32 v[116:117], s[0:1], v158, s95, v[138:139]
	global_store_dwordx4 v[116:117], v[112:115], off
	s_nop 1
	v_fmamk_f32 v112, v159, 0x3a000000, v239
	v_rsq_f32_e32 v112, v112
	s_nop 0
	v_mul_f32_e32 v114, v112, v112
	v_mul_f32_e32 v112, 0xbfb8aa3b, v112
	v_pk_mul_f32 v[108:109], v[108:109], v[112:113] op_sel_hi:[1,0]
	v_pk_mul_f32 v[104:105], v[104:105], v[114:115] op_sel_hi:[1,0]
	v_exp_f32_e32 v108, v108
	v_exp_f32_e32 v109, v109
	v_pk_mul_f32 v[96:97], v[96:97], v[112:113] op_sel_hi:[1,0]
	v_pk_mul_f32 v[98:99], v[98:99], v[112:113] op_sel_hi:[1,0]
	v_exp_f32_e32 v96, v96
	v_pk_add_f32 v[108:109], v[108:109], 1.0 op_sel_hi:[1,0]
	v_exp_f32_e32 v97, v97
	v_rcp_f32_e32 v108, v108
	v_rcp_f32_e32 v109, v109
	v_exp_f32_e32 v98, v98
	v_exp_f32_e32 v99, v99
	v_pk_add_f32 v[96:97], v[96:97], 1.0 op_sel_hi:[1,0]
	v_pk_mul_f32 v[104:105], v[104:105], v[108:109]
	v_pk_mul_f32 v[108:109], v[110:111], v[112:113] op_sel_hi:[1,0]
	v_rcp_f32_e32 v96, v96
	v_exp_f32_e32 v108, v108
	v_exp_f32_e32 v109, v109
	v_rcp_f32_e32 v97, v97
	v_pk_add_f32 v[98:99], v[98:99], 1.0 op_sel_hi:[1,0]
	v_pk_mul_f32 v[100:101], v[100:101], v[114:115] op_sel_hi:[1,0]
	v_pk_add_f32 v[108:109], v[108:109], 1.0 op_sel_hi:[1,0]
	v_rcp_f32_e32 v98, v98
	v_rcp_f32_e32 v108, v108
	v_rcp_f32_e32 v109, v109
	v_rcp_f32_e32 v99, v99
	v_pk_mul_f32 v[106:107], v[106:107], v[114:115] op_sel_hi:[1,0]
	v_pk_mul_f32 v[100:101], v[100:101], v[96:97]
	v_pk_mul_f32 v[96:97], v[102:103], v[114:115] op_sel_hi:[1,0]
	v_pk_mul_f32 v[106:107], v[106:107], v[108:109]
	v_pk_mul_f32 v[102:103], v[96:97], v[98:99]
	v_cvt_pk_bf16_f32 v96, v104, v105
	v_cvt_pk_bf16_f32 v97, v106, v107
	v_cvt_pk_bf16_f32 v98, v100, v101
	v_cvt_pk_bf16_f32 v99, v102, v103
	v_mad_i64_i32 v[100:101], s[0:1], v144, s95, v[138:139]
	global_store_dwordx4 v[100:101], v[96:99], off
	s_nop 1
	v_fmamk_f32 v96, v156, 0x3a000000, v239
	v_rsq_f32_e32 v97, v96
	s_nop 0
	v_mul_f32_e32 v98, 0xbfb8aa3b, v97
	v_pk_mul_f32 v[88:89], v[88:89], v[98:99] op_sel_hi:[1,0]
	v_pk_mul_f32 v[80:81], v[80:81], v[98:99] op_sel_hi:[1,0]
	v_exp_f32_e32 v88, v88
	v_exp_f32_e32 v89, v89
	v_pk_mul_f32 v[90:91], v[90:91], v[98:99] op_sel_hi:[1,0]
	v_exp_f32_e32 v80, v80
	v_exp_f32_e32 v81, v81
	v_pk_mul_f32 v[82:83], v[82:83], v[98:99] op_sel_hi:[1,0]
	v_exp_f32_e32 v90, v90
	v_exp_f32_e32 v91, v91
	v_exp_f32_e32 v82, v82
	v_exp_f32_e32 v83, v83
	v_pk_add_f32 v[88:89], v[88:89], 1.0 op_sel_hi:[1,0]
	v_pk_add_f32 v[80:81], v[80:81], 1.0 op_sel_hi:[1,0]
	v_rcp_f32_e32 v88, v88
	v_rcp_f32_e32 v89, v89
	v_pk_add_f32 v[90:91], v[90:91], 1.0 op_sel_hi:[1,0]
	v_rcp_f32_e32 v80, v80
	v_rcp_f32_e32 v81, v81
	v_pk_add_f32 v[82:83], v[82:83], 1.0 op_sel_hi:[1,0]
	v_rcp_f32_e32 v90, v90
	v_rcp_f32_e32 v91, v91
	v_rcp_f32_e32 v82, v82
	v_rcp_f32_e32 v83, v83
	v_mul_f32_e32 v96, v97, v97
	v_pk_mul_f32 v[92:93], v[92:93], v[96:97] op_sel_hi:[1,0]
	v_pk_mul_f32 v[84:85], v[84:85], v[96:97] op_sel_hi:[1,0]
	v_pk_mul_f32 v[88:89], v[92:93], v[88:89]
	v_pk_mul_f32 v[92:93], v[94:95], v[96:97] op_sel_hi:[1,0]
	v_pk_mul_f32 v[84:85], v[84:85], v[80:81]
	v_pk_mul_f32 v[80:81], v[86:87], v[96:97] op_sel_hi:[1,0]
	v_pk_mul_f32 v[90:91], v[92:93], v[90:91]
	v_pk_mul_f32 v[86:87], v[80:81], v[82:83]
	v_cvt_pk_bf16_f32 v80, v88, v89
	v_cvt_pk_bf16_f32 v81, v90, v91
	v_cvt_pk_bf16_f32 v82, v84, v85
	v_cvt_pk_bf16_f32 v83, v86, v87
	v_mad_i64_i32 v[84:85], s[0:1], v142, s95, v[138:139]
	global_store_dwordx4 v[84:85], v[80:83], off
	s_nop 1
	v_fmamk_f32 v80, v155, 0x3a000000, v239
	v_rsq_f32_e32 v81, v80
	s_nop 0
	v_mul_f32_e32 v82, 0xbfb8aa3b, v81
	v_pk_mul_f32 v[72:73], v[72:73], v[82:83] op_sel_hi:[1,0]
	v_pk_mul_f32 v[64:65], v[64:65], v[82:83] op_sel_hi:[1,0]
	v_exp_f32_e32 v72, v72
	v_exp_f32_e32 v73, v73
	v_pk_mul_f32 v[74:75], v[74:75], v[82:83] op_sel_hi:[1,0]
	v_exp_f32_e32 v64, v64
	v_exp_f32_e32 v65, v65
	v_pk_mul_f32 v[66:67], v[66:67], v[82:83] op_sel_hi:[1,0]
	v_exp_f32_e32 v74, v74
	v_exp_f32_e32 v75, v75
	v_exp_f32_e32 v66, v66
	v_exp_f32_e32 v67, v67
	v_pk_add_f32 v[72:73], v[72:73], 1.0 op_sel_hi:[1,0]
	v_pk_add_f32 v[64:65], v[64:65], 1.0 op_sel_hi:[1,0]
	v_rcp_f32_e32 v72, v72
	v_rcp_f32_e32 v73, v73
	v_pk_add_f32 v[74:75], v[74:75], 1.0 op_sel_hi:[1,0]
	v_rcp_f32_e32 v64, v64
	v_rcp_f32_e32 v65, v65
	v_pk_add_f32 v[66:67], v[66:67], 1.0 op_sel_hi:[1,0]
	v_rcp_f32_e32 v74, v74
	v_rcp_f32_e32 v75, v75
	v_rcp_f32_e32 v66, v66
	v_rcp_f32_e32 v67, v67
	v_mul_f32_e32 v80, v81, v81
	v_pk_mul_f32 v[76:77], v[76:77], v[80:81] op_sel_hi:[1,0]
	v_pk_mul_f32 v[68:69], v[68:69], v[80:81] op_sel_hi:[1,0]
	v_pk_mul_f32 v[72:73], v[76:77], v[72:73]
	v_pk_mul_f32 v[76:77], v[78:79], v[80:81] op_sel_hi:[1,0]
	v_pk_mul_f32 v[68:69], v[68:69], v[64:65]
	v_pk_mul_f32 v[64:65], v[70:71], v[80:81] op_sel_hi:[1,0]
	v_pk_mul_f32 v[74:75], v[76:77], v[74:75]
	v_pk_mul_f32 v[70:71], v[64:65], v[66:67]
	v_cvt_pk_bf16_f32 v64, v72, v73
	v_cvt_pk_bf16_f32 v65, v74, v75
	v_cvt_pk_bf16_f32 v66, v68, v69
	v_cvt_pk_bf16_f32 v67, v70, v71
	v_mad_i64_i32 v[68:69], s[0:1], v140, s95, v[138:139]
	global_store_dwordx4 v[68:69], v[64:67], off
	s_nop 1
	v_fmamk_f32 v64, v154, 0x3a000000, v239
	v_rsq_f32_e32 v65, v64
	s_nop 0
	v_mul_f32_e32 v66, 0xbfb8aa3b, v65
	v_pk_mul_f32 v[56:57], v[56:57], v[66:67] op_sel_hi:[1,0]
	v_pk_mul_f32 v[48:49], v[48:49], v[66:67] op_sel_hi:[1,0]
	v_exp_f32_e32 v56, v56
	v_exp_f32_e32 v57, v57
	v_pk_mul_f32 v[58:59], v[58:59], v[66:67] op_sel_hi:[1,0]
	v_exp_f32_e32 v48, v48
	v_exp_f32_e32 v49, v49
	v_pk_mul_f32 v[50:51], v[50:51], v[66:67] op_sel_hi:[1,0]
	v_exp_f32_e32 v58, v58
	v_exp_f32_e32 v59, v59
	v_exp_f32_e32 v50, v50
	v_exp_f32_e32 v51, v51
	v_pk_add_f32 v[56:57], v[56:57], 1.0 op_sel_hi:[1,0]
	v_pk_add_f32 v[48:49], v[48:49], 1.0 op_sel_hi:[1,0]
	v_rcp_f32_e32 v56, v56
	v_rcp_f32_e32 v57, v57
	v_pk_add_f32 v[58:59], v[58:59], 1.0 op_sel_hi:[1,0]
	v_rcp_f32_e32 v48, v48
	v_rcp_f32_e32 v49, v49
	v_pk_add_f32 v[50:51], v[50:51], 1.0 op_sel_hi:[1,0]
	v_rcp_f32_e32 v58, v58
	v_rcp_f32_e32 v59, v59
	v_rcp_f32_e32 v50, v50
	v_rcp_f32_e32 v51, v51
	v_mul_f32_e32 v64, v65, v65
	v_pk_mul_f32 v[60:61], v[60:61], v[64:65] op_sel_hi:[1,0]
	v_pk_mul_f32 v[52:53], v[52:53], v[64:65] op_sel_hi:[1,0]
	v_pk_mul_f32 v[56:57], v[60:61], v[56:57]
	v_pk_mul_f32 v[60:61], v[62:63], v[64:65] op_sel_hi:[1,0]
	v_pk_mul_f32 v[52:53], v[52:53], v[48:49]
	v_pk_mul_f32 v[48:49], v[54:55], v[64:65] op_sel_hi:[1,0]
	v_pk_mul_f32 v[58:59], v[60:61], v[58:59]
	v_pk_mul_f32 v[54:55], v[48:49], v[50:51]
	v_cvt_pk_bf16_f32 v48, v56, v57
	v_cvt_pk_bf16_f32 v49, v58, v59
	v_cvt_pk_bf16_f32 v50, v52, v53
	v_cvt_pk_bf16_f32 v51, v54, v55
	v_mad_i64_i32 v[52:53], s[0:1], v153, s95, v[138:139]
	global_store_dwordx4 v[52:53], v[48:51], off
	s_nop 1
	v_fmamk_f32 v48, v152, 0x3a000000, v239
	v_rsq_f32_e32 v49, v48
	s_nop 0
	v_mul_f32_e32 v50, 0xbfb8aa3b, v49
	v_pk_mul_f32 v[40:41], v[40:41], v[50:51] op_sel_hi:[1,0]
	v_pk_mul_f32 v[32:33], v[32:33], v[50:51] op_sel_hi:[1,0]
	v_exp_f32_e32 v40, v40
	v_exp_f32_e32 v41, v41
	v_pk_mul_f32 v[42:43], v[42:43], v[50:51] op_sel_hi:[1,0]
	v_exp_f32_e32 v32, v32
	v_exp_f32_e32 v33, v33
	v_pk_mul_f32 v[34:35], v[34:35], v[50:51] op_sel_hi:[1,0]
	v_exp_f32_e32 v42, v42
	v_exp_f32_e32 v43, v43
	v_exp_f32_e32 v34, v34
	v_exp_f32_e32 v35, v35
	v_pk_add_f32 v[40:41], v[40:41], 1.0 op_sel_hi:[1,0]
	v_pk_add_f32 v[32:33], v[32:33], 1.0 op_sel_hi:[1,0]
	v_rcp_f32_e32 v40, v40
	v_rcp_f32_e32 v41, v41
	v_pk_add_f32 v[42:43], v[42:43], 1.0 op_sel_hi:[1,0]
	v_rcp_f32_e32 v32, v32
	v_rcp_f32_e32 v33, v33
	v_pk_add_f32 v[34:35], v[34:35], 1.0 op_sel_hi:[1,0]
	v_rcp_f32_e32 v42, v42
	v_rcp_f32_e32 v43, v43
	v_rcp_f32_e32 v34, v34
	v_rcp_f32_e32 v35, v35
	v_mul_f32_e32 v48, v49, v49
	v_pk_mul_f32 v[44:45], v[44:45], v[48:49] op_sel_hi:[1,0]
	v_pk_mul_f32 v[36:37], v[36:37], v[48:49] op_sel_hi:[1,0]
	v_pk_mul_f32 v[40:41], v[44:45], v[40:41]
	v_pk_mul_f32 v[44:45], v[46:47], v[48:49] op_sel_hi:[1,0]
	v_pk_mul_f32 v[36:37], v[36:37], v[32:33]
	v_pk_mul_f32 v[32:33], v[38:39], v[48:49] op_sel_hi:[1,0]
	v_pk_mul_f32 v[42:43], v[44:45], v[42:43]
	v_pk_mul_f32 v[38:39], v[32:33], v[34:35]
	v_cvt_pk_bf16_f32 v32, v40, v41
	v_cvt_pk_bf16_f32 v33, v42, v43
	v_cvt_pk_bf16_f32 v34, v36, v37
	v_cvt_pk_bf16_f32 v35, v38, v39
	v_mad_i64_i32 v[36:37], s[0:1], v151, s95, v[138:139]
	global_store_dwordx4 v[36:37], v[32:35], off
	s_nop 1
	v_fmamk_f32 v32, v150, 0x3a000000, v239
	v_rsq_f32_e32 v33, v32
	s_nop 0
	v_mul_f32_e32 v34, 0xbfb8aa3b, v33
	v_pk_mul_f32 v[24:25], v[24:25], v[34:35] op_sel_hi:[1,0]
	v_pk_mul_f32 v[16:17], v[16:17], v[34:35] op_sel_hi:[1,0]
	v_exp_f32_e32 v24, v24
	v_exp_f32_e32 v25, v25
	v_pk_mul_f32 v[26:27], v[26:27], v[34:35] op_sel_hi:[1,0]
	v_exp_f32_e32 v16, v16
	v_exp_f32_e32 v17, v17
	v_pk_mul_f32 v[18:19], v[18:19], v[34:35] op_sel_hi:[1,0]
	v_exp_f32_e32 v26, v26
	v_exp_f32_e32 v27, v27
	v_exp_f32_e32 v18, v18
	v_exp_f32_e32 v19, v19
	v_pk_add_f32 v[24:25], v[24:25], 1.0 op_sel_hi:[1,0]
	v_pk_add_f32 v[16:17], v[16:17], 1.0 op_sel_hi:[1,0]
	v_rcp_f32_e32 v24, v24
	v_rcp_f32_e32 v25, v25
	v_pk_add_f32 v[26:27], v[26:27], 1.0 op_sel_hi:[1,0]
	v_rcp_f32_e32 v16, v16
	v_rcp_f32_e32 v17, v17
	v_pk_add_f32 v[18:19], v[18:19], 1.0 op_sel_hi:[1,0]
	v_rcp_f32_e32 v26, v26
	v_rcp_f32_e32 v27, v27
	v_rcp_f32_e32 v18, v18
	v_rcp_f32_e32 v19, v19
	v_mul_f32_e32 v32, v33, v33
	v_pk_mul_f32 v[28:29], v[28:29], v[32:33] op_sel_hi:[1,0]
	v_pk_mul_f32 v[20:21], v[20:21], v[32:33] op_sel_hi:[1,0]
	v_pk_mul_f32 v[24:25], v[28:29], v[24:25]
	v_pk_mul_f32 v[28:29], v[30:31], v[32:33] op_sel_hi:[1,0]
	v_pk_mul_f32 v[20:21], v[20:21], v[16:17]
	v_pk_mul_f32 v[16:17], v[22:23], v[32:33] op_sel_hi:[1,0]
	v_pk_mul_f32 v[26:27], v[28:29], v[26:27]
	v_pk_mul_f32 v[22:23], v[16:17], v[18:19]
	v_cvt_pk_bf16_f32 v16, v24, v25
	v_cvt_pk_bf16_f32 v17, v26, v27
	v_cvt_pk_bf16_f32 v18, v20, v21
	v_cvt_pk_bf16_f32 v19, v22, v23
	v_mad_i64_i32 v[20:21], s[0:1], v145, s95, v[138:139]
	global_store_dwordx4 v[20:21], v[16:19], off
	s_nop 1
	v_fmamk_f32 v16, v143, 0x3a000000, v239
	v_rsq_f32_e32 v17, v16
	s_nop 0
	v_mul_f32_e32 v18, 0xbfb8aa3b, v17
	v_pk_mul_f32 v[8:9], v[8:9], v[18:19] op_sel_hi:[1,0]
	v_pk_mul_f32 v[0:1], v[0:1], v[18:19] op_sel_hi:[1,0]
	v_exp_f32_e32 v8, v8
	v_exp_f32_e32 v9, v9
	v_pk_mul_f32 v[10:11], v[10:11], v[18:19] op_sel_hi:[1,0]
	v_exp_f32_e32 v0, v0
	v_exp_f32_e32 v1, v1
	v_pk_mul_f32 v[2:3], v[2:3], v[18:19] op_sel_hi:[1,0]
	v_exp_f32_e32 v10, v10
	v_exp_f32_e32 v11, v11
	v_exp_f32_e32 v2, v2
	v_exp_f32_e32 v3, v3
	v_pk_add_f32 v[8:9], v[8:9], 1.0 op_sel_hi:[1,0]
	v_pk_add_f32 v[0:1], v[0:1], 1.0 op_sel_hi:[1,0]
	v_rcp_f32_e32 v8, v8
	v_rcp_f32_e32 v9, v9
	v_pk_add_f32 v[10:11], v[10:11], 1.0 op_sel_hi:[1,0]
	v_rcp_f32_e32 v0, v0
	v_rcp_f32_e32 v1, v1
	v_pk_add_f32 v[2:3], v[2:3], 1.0 op_sel_hi:[1,0]
	v_rcp_f32_e32 v10, v10
	v_rcp_f32_e32 v11, v11
	v_rcp_f32_e32 v2, v2
	v_rcp_f32_e32 v3, v3
	v_mul_f32_e32 v16, v17, v17
	v_pk_mul_f32 v[12:13], v[12:13], v[16:17] op_sel_hi:[1,0]
	v_pk_mul_f32 v[4:5], v[4:5], v[16:17] op_sel_hi:[1,0]
	v_pk_mul_f32 v[8:9], v[12:13], v[8:9]
	v_pk_mul_f32 v[12:13], v[14:15], v[16:17] op_sel_hi:[1,0]
	v_pk_mul_f32 v[4:5], v[4:5], v[0:1]
	v_pk_mul_f32 v[0:1], v[6:7], v[16:17] op_sel_hi:[1,0]
	v_pk_mul_f32 v[10:11], v[12:13], v[10:11]
	v_pk_mul_f32 v[6:7], v[0:1], v[2:3]
	v_cvt_pk_bf16_f32 v0, v8, v9
	v_cvt_pk_bf16_f32 v1, v10, v11
	v_cvt_pk_bf16_f32 v2, v4, v5
	v_cvt_pk_bf16_f32 v3, v6, v7
	v_mad_i64_i32 v[4:5], s[0:1], v141, s95, v[138:139]
	global_store_dwordx4 v[4:5], v[0:3], off
	s_waitcnt vmcnt(8)
	s_cbranch_vccnz .LBB0_524
	s_andn2_b64 vcc, exec, s[8:9]
	s_cbranch_vccnz .LBB0_523
	s_barrier
	s_branch .LBB0_523
